# GEMM K-loops: LDS-DMA uses SGPR base + 32-bit VGPR offset (removes 16 v_lshl_add_u64 per iteration) on top of v40
# speedup vs baseline: 1.0045x; 1.0045x over previous
.LBB0_92:
	s_add_i32 s21, s20, 2
	s_add_u32 s12, s28, 0x80
	s_addc_u32 s13, s29, 0
	s_add_i32 s36, 0, 0x10000
	s_cmp_eq_u32 s1, s20
	s_cselect_b32 s59, s5, s13
	s_cselect_b32 s58, s4, s12
	s_cselect_b32 s13, s57, s19
	s_cselect_b32 s12, s56, s18
	s_add_i32 s20, 0, 0x14000
	v_add_u32_e32 v60, s36, v175
	v_add_u32_e32 v76, s20, v175
	ds_read_b128 v[48:51], v60
	ds_read_b128 v[52:55], v60 offset:1024
	ds_read_b128 v[56:59], v60 offset:2048
	ds_read_b128 v[60:63], v60 offset:3072
	ds_read_b128 v[64:67], v76
	ds_read_b128 v[68:71], v76 offset:1024
	ds_read_b128 v[72:75], v76 offset:2048
	ds_read_b128 v[76:79], v76 offset:3072
	s_add_i32 m0, s72, 0xc000
	ds_read_b128 v[170:173], v177
	ds_read_b128 v[178:181], v177 offset:1024
	ds_read_b128 v[182:185], v177 offset:2048
	ds_read_b128 v[186:189], v177 offset:3072
	ds_read_b128 v[194:197], v177 offset:4096
	ds_read_b128 v[198:201], v177 offset:5120
	ds_read_b128 v[202:205], v177 offset:6144
	ds_read_b128 v[212:215], v177 offset:7168
	global_load_lds_dwordx4 v166, s[28:29]
	s_add_i32 m0, s72, 0xe000
	s_nop 0
	global_load_lds_dwordx4 v168, s[28:29]
	s_waitcnt vmcnt(8)
	s_waitcnt lgkmcnt(0)
	s_barrier
	s_setprio 1
	v_mfma_f32_16x16x32_bf16 v[156:159], v[48:51], v[170:173], v[156:159]
	v_mfma_f32_16x16x32_bf16 v[152:155], v[56:59], v[170:173], v[152:155]
	v_mfma_f32_16x16x32_bf16 v[140:143], v[48:51], v[182:185], v[140:143]
	v_mfma_f32_16x16x32_bf16 v[136:139], v[56:59], v[182:185], v[136:139]
	v_mfma_f32_16x16x32_bf16 v[124:127], v[48:51], v[194:197], v[124:127]
	v_mfma_f32_16x16x32_bf16 v[120:123], v[56:59], v[194:197], v[120:123]
	v_mfma_f32_16x16x32_bf16 v[108:111], v[48:51], v[202:205], v[108:111]
	v_mfma_f32_16x16x32_bf16 v[104:107], v[56:59], v[202:205], v[104:107]
	v_mfma_f32_16x16x32_bf16 v[156:159], v[52:55], v[178:181], v[156:159]
	v_mfma_f32_16x16x32_bf16 v[152:155], v[60:63], v[178:181], v[152:155]
	v_mfma_f32_16x16x32_bf16 v[140:143], v[52:55], v[186:189], v[140:143]
	v_mfma_f32_16x16x32_bf16 v[136:139], v[60:63], v[186:189], v[136:139]
	v_mfma_f32_16x16x32_bf16 v[124:127], v[52:55], v[198:201], v[124:127]
	v_mfma_f32_16x16x32_bf16 v[120:123], v[60:63], v[198:201], v[120:123]
	v_mfma_f32_16x16x32_bf16 v[108:111], v[52:55], v[212:215], v[108:111]
	v_mfma_f32_16x16x32_bf16 v[104:107], v[60:63], v[212:215], v[104:107]
	v_mfma_f32_16x16x32_bf16 v[148:151], v[64:67], v[170:173], v[148:151]
	v_mfma_f32_16x16x32_bf16 v[144:147], v[72:75], v[170:173], v[144:147]
	v_mfma_f32_16x16x32_bf16 v[132:135], v[64:67], v[182:185], v[132:135]
	v_mfma_f32_16x16x32_bf16 v[128:131], v[72:75], v[182:185], v[128:131]
	v_mfma_f32_16x16x32_bf16 v[116:119], v[64:67], v[194:197], v[116:119]
	v_mfma_f32_16x16x32_bf16 v[112:115], v[72:75], v[194:197], v[112:115]
	v_mfma_f32_16x16x32_bf16 v[100:103], v[64:67], v[202:205], v[100:103]
	v_mfma_f32_16x16x32_bf16 v[96:99], v[72:75], v[202:205], v[96:99]
	v_mfma_f32_16x16x32_bf16 v[148:151], v[68:71], v[178:181], v[148:151]
	v_mfma_f32_16x16x32_bf16 v[144:147], v[76:79], v[178:181], v[144:147]
	v_mfma_f32_16x16x32_bf16 v[132:135], v[68:71], v[186:189], v[132:135]
	v_mfma_f32_16x16x32_bf16 v[128:131], v[76:79], v[186:189], v[128:131]
	v_mfma_f32_16x16x32_bf16 v[116:119], v[68:71], v[198:201], v[116:119]
	v_mfma_f32_16x16x32_bf16 v[112:115], v[76:79], v[198:201], v[112:115]
	v_mfma_f32_16x16x32_bf16 v[100:103], v[68:71], v[212:215], v[100:103]
	v_mfma_f32_16x16x32_bf16 v[96:99], v[76:79], v[212:215], v[96:99]
	s_setprio 0
	s_barrier
	s_add_i32 s36, s36, s9
	s_mov_b64 vcc, s[12:13]
	s_mov_b32 m0, s36
	ds_read_b128 v[170:173], v177 offset:16384
	ds_read_b128 v[178:181], v177 offset:17408
	ds_read_b128 v[182:185], v177 offset:18432
	ds_read_b128 v[186:189], v177 offset:19456
	ds_read_b128 v[194:197], v177 offset:20480
	ds_read_b128 v[198:201], v177 offset:21504
	ds_read_b128 v[202:205], v177 offset:22528
	ds_read_b128 v[212:215], v177 offset:23552
	global_load_lds_dwordx4 v192, s[12:13]
	s_add_i32 m0, s36, 0x2000
	s_add_i32 s20, s20, s9
	global_load_lds_dwordx4 v160, s[12:13]
	s_add_u32 s12, s12, s10
	s_addc_u32 s13, s13, 0
	s_mov_b32 m0, s20
	s_nop 0
	global_load_lds_dwordx4 v192, s[12:13]
	s_add_i32 m0, s20, 0x2000
	s_nop 0
	global_load_lds_dwordx4 v160, s[12:13]
	s_mov_b32 m0, s72
	s_nop 0
	global_load_lds_dwordx4 v164, s[58:59]
	s_mov_b32 m0, s73
	s_nop 0
	global_load_lds_dwordx4 v162, s[58:59]
	s_waitcnt vmcnt(8)
	s_waitcnt lgkmcnt(0)
	s_barrier
	s_setprio 1
	v_mfma_f32_16x16x32_bf16 v[92:95], v[48:51], v[170:173], v[92:95]
	v_mfma_f32_16x16x32_bf16 v[88:91], v[56:59], v[170:173], v[88:91]
	v_mfma_f32_16x16x32_bf16 v[44:47], v[48:51], v[182:185], v[44:47]
	v_mfma_f32_16x16x32_bf16 v[40:43], v[56:59], v[182:185], v[40:43]
	v_mfma_f32_16x16x32_bf16 v[28:31], v[48:51], v[194:197], v[28:31]
	v_mfma_f32_16x16x32_bf16 v[24:27], v[56:59], v[194:197], v[24:27]
	v_mfma_f32_16x16x32_bf16 v[12:15], v[48:51], v[202:205], v[12:15]
	v_mfma_f32_16x16x32_bf16 v[8:11], v[56:59], v[202:205], v[8:11]
	v_mfma_f32_16x16x32_bf16 v[92:95], v[52:55], v[178:181], v[92:95]
	v_mfma_f32_16x16x32_bf16 v[88:91], v[60:63], v[178:181], v[88:91]
	v_mfma_f32_16x16x32_bf16 v[44:47], v[52:55], v[186:189], v[44:47]
	v_mfma_f32_16x16x32_bf16 v[40:43], v[60:63], v[186:189], v[40:43]
	v_mfma_f32_16x16x32_bf16 v[28:31], v[52:55], v[198:201], v[28:31]
	v_mfma_f32_16x16x32_bf16 v[24:27], v[60:63], v[198:201], v[24:27]
	v_mfma_f32_16x16x32_bf16 v[12:15], v[52:55], v[212:215], v[12:15]
	v_mfma_f32_16x16x32_bf16 v[8:11], v[60:63], v[212:215], v[8:11]
	v_mfma_f32_16x16x32_bf16 v[36:39], v[64:67], v[182:185], v[36:39]
	v_mfma_f32_16x16x32_bf16 v[32:35], v[72:75], v[182:185], v[32:35]
	v_mfma_f32_16x16x32_bf16 v[20:23], v[64:67], v[194:197], v[20:23]
	v_mfma_f32_16x16x32_bf16 v[16:19], v[72:75], v[194:197], v[16:19]
	v_mfma_f32_16x16x32_bf16 v[4:7], v[64:67], v[202:205], v[4:7]
	v_mfma_f32_16x16x32_bf16 v[0:3], v[72:75], v[202:205], v[0:3]
	v_mfma_f32_16x16x32_bf16 v[48:51], v[64:67], v[170:173], v[84:87]
	v_mfma_f32_16x16x32_bf16 v[52:55], v[72:75], v[170:173], v[80:83]
	v_mfma_f32_16x16x32_bf16 v[36:39], v[68:71], v[186:189], v[36:39]
	v_mfma_f32_16x16x32_bf16 v[32:35], v[76:79], v[186:189], v[32:35]
	v_mfma_f32_16x16x32_bf16 v[20:23], v[68:71], v[198:201], v[20:23]
	v_mfma_f32_16x16x32_bf16 v[16:19], v[76:79], v[198:201], v[16:19]
	v_mfma_f32_16x16x32_bf16 v[4:7], v[68:71], v[212:215], v[4:7]
	v_mfma_f32_16x16x32_bf16 v[0:3], v[76:79], v[212:215], v[0:3]
	v_mfma_f32_16x16x32_bf16 v[48:51], v[68:71], v[178:181], v[48:51]
	v_mfma_f32_16x16x32_bf16 v[52:55], v[76:79], v[178:181], v[52:55]
	s_setprio 0
	s_barrier
	s_add_i32 s20, 0, 0x18000
	s_add_i32 s36, 0, 0x1c000
	v_add_u32_e32 v68, s20, v175
	v_add_u32_e32 v80, s36, v175
	ds_read_b128 v[56:59], v68
	ds_read_b128 v[60:63], v68 offset:1024
	ds_read_b128 v[64:67], v68 offset:2048
	ds_read_b128 v[68:71], v68 offset:3072
	ds_read_b128 v[72:75], v80
	ds_read_b128 v[76:79], v80 offset:1024
	ds_read_b128 v[170:173], v80 offset:2048
	ds_read_b128 v[178:181], v80 offset:3072
	s_add_u32 s12, s58, s30
	s_addc_u32 s13, s59, 0
	s_mov_b32 m0, s74
	ds_read_b128 v[80:83], v177 offset:32768
	ds_read_b128 v[84:87], v177 offset:33792
	ds_read_b128 v[182:185], v177 offset:34816
	ds_read_b128 v[186:189], v177 offset:35840
	ds_read_b128 v[194:197], v177 offset:36864
	ds_read_b128 v[198:201], v177 offset:37888
	ds_read_b128 v[202:205], v177 offset:38912
	ds_read_b128 v[212:215], v177 offset:39936
	global_load_lds_dwordx4 v164, s[12:13]
	s_mov_b32 m0, s75
	s_nop 0
	global_load_lds_dwordx4 v162, s[12:13]
	s_waitcnt vmcnt(8)
	s_waitcnt lgkmcnt(0)
	s_barrier
	s_setprio 1
	v_mfma_f32_16x16x32_bf16 v[156:159], v[56:59], v[80:83], v[156:159]
	v_mfma_f32_16x16x32_bf16 v[152:155], v[64:67], v[80:83], v[152:155]
	v_mfma_f32_16x16x32_bf16 v[140:143], v[56:59], v[182:185], v[140:143]
	v_mfma_f32_16x16x32_bf16 v[136:139], v[64:67], v[182:185], v[136:139]
	v_mfma_f32_16x16x32_bf16 v[124:127], v[56:59], v[194:197], v[124:127]
	v_mfma_f32_16x16x32_bf16 v[120:123], v[64:67], v[194:197], v[120:123]
	v_mfma_f32_16x16x32_bf16 v[108:111], v[56:59], v[202:205], v[108:111]
	v_mfma_f32_16x16x32_bf16 v[104:107], v[64:67], v[202:205], v[104:107]
	v_mfma_f32_16x16x32_bf16 v[156:159], v[60:63], v[84:87], v[156:159]
	v_mfma_f32_16x16x32_bf16 v[152:155], v[68:71], v[84:87], v[152:155]
	v_mfma_f32_16x16x32_bf16 v[140:143], v[60:63], v[186:189], v[140:143]
	v_mfma_f32_16x16x32_bf16 v[136:139], v[68:71], v[186:189], v[136:139]
	v_mfma_f32_16x16x32_bf16 v[124:127], v[60:63], v[198:201], v[124:127]
	v_mfma_f32_16x16x32_bf16 v[120:123], v[68:71], v[198:201], v[120:123]
	v_mfma_f32_16x16x32_bf16 v[108:111], v[60:63], v[212:215], v[108:111]
	v_mfma_f32_16x16x32_bf16 v[104:107], v[68:71], v[212:215], v[104:107]
	v_mfma_f32_16x16x32_bf16 v[148:151], v[72:75], v[80:83], v[148:151]
	v_mfma_f32_16x16x32_bf16 v[80:83], v[170:173], v[80:83], v[144:147]
	v_mfma_f32_16x16x32_bf16 v[144:147], v[178:181], v[84:87], v[80:83]
	v_mfma_f32_16x16x32_bf16 v[80:83], v[72:75], v[182:185], v[132:135]
	v_mfma_f32_16x16x32_bf16 v[132:135], v[76:79], v[186:189], v[80:83]
	v_mfma_f32_16x16x32_bf16 v[80:83], v[170:173], v[182:185], v[128:131]
	v_mfma_f32_16x16x32_bf16 v[128:131], v[178:181], v[186:189], v[80:83]
	v_mfma_f32_16x16x32_bf16 v[80:83], v[72:75], v[194:197], v[116:119]
	v_mfma_f32_16x16x32_bf16 v[116:119], v[76:79], v[198:201], v[80:83]
	v_mfma_f32_16x16x32_bf16 v[80:83], v[170:173], v[194:197], v[112:115]
	v_mfma_f32_16x16x32_bf16 v[112:115], v[178:181], v[198:201], v[80:83]
	v_mfma_f32_16x16x32_bf16 v[80:83], v[72:75], v[202:205], v[100:103]
	v_mfma_f32_16x16x32_bf16 v[100:103], v[76:79], v[212:215], v[80:83]
	v_mfma_f32_16x16x32_bf16 v[80:83], v[170:173], v[202:205], v[96:99]
	v_mfma_f32_16x16x32_bf16 v[148:151], v[76:79], v[84:87], v[148:151]
	v_mfma_f32_16x16x32_bf16 v[96:99], v[178:181], v[212:215], v[80:83]
	s_setprio 0
	s_barrier
	s_add_i32 m0, s20, s9
	s_add_u32 s12, vcc_lo, 0x80
	s_addc_u32 s13, vcc_hi, 0
	ds_read_b128 v[80:83], v177 offset:49152
	ds_read_b128 v[182:185], v177 offset:50176
	ds_read_b128 v[186:189], v177 offset:51200
	ds_read_b128 v[194:197], v177 offset:52224
	ds_read_b128 v[198:201], v177 offset:53248
	ds_read_b128 v[202:205], v177 offset:54272
	ds_read_b128 v[212:215], v177 offset:55296
	ds_read_b128 v[242:245], v177 offset:56320
	global_load_lds_dwordx4 v192, s[12:13]
	s_add_i32 m0, m0, 0x2000
	s_nop 0
	global_load_lds_dwordx4 v160, s[12:13]
	s_add_u32 s12, s12, s10
	s_addc_u32 s13, s13, 0
	s_add_i32 m0, s36, s9
	s_nop 0
	global_load_lds_dwordx4 v192, s[12:13]
	s_add_i32 m0, m0, 0x2000
	s_nop 0
	global_load_lds_dwordx4 v160, s[12:13]
	s_add_u32 s12, s58, 0x80
	s_addc_u32 s13, s59, 0
	s_mov_b32 m0, s76
	s_nop 0
	global_load_lds_dwordx4 v164, s[12:13]
	s_mov_b32 m0, s77
	s_nop 0
	global_load_lds_dwordx4 v162, s[12:13]
	s_waitcnt vmcnt(8)
	s_waitcnt lgkmcnt(0)
	s_barrier
	s_setprio 1
	v_mfma_f32_16x16x32_bf16 v[84:87], v[56:59], v[80:83], v[92:95]
	v_mfma_f32_16x16x32_bf16 v[92:95], v[60:63], v[182:185], v[84:87]
	v_mfma_f32_16x16x32_bf16 v[84:87], v[64:67], v[80:83], v[88:91]
	v_mfma_f32_16x16x32_bf16 v[44:47], v[56:59], v[186:189], v[44:47]
	v_mfma_f32_16x16x32_bf16 v[40:43], v[64:67], v[186:189], v[40:43]
	v_mfma_f32_16x16x32_bf16 v[28:31], v[56:59], v[198:201], v[28:31]
	v_mfma_f32_16x16x32_bf16 v[24:27], v[64:67], v[198:201], v[24:27]
	v_mfma_f32_16x16x32_bf16 v[12:15], v[56:59], v[212:215], v[12:15]
	v_mfma_f32_16x16x32_bf16 v[8:11], v[64:67], v[212:215], v[8:11]
	v_mfma_f32_16x16x32_bf16 v[88:91], v[68:71], v[182:185], v[84:87]
	v_mfma_f32_16x16x32_bf16 v[44:47], v[60:63], v[194:197], v[44:47]
	v_mfma_f32_16x16x32_bf16 v[40:43], v[68:71], v[194:197], v[40:43]
	v_mfma_f32_16x16x32_bf16 v[28:31], v[60:63], v[202:205], v[28:31]
	v_mfma_f32_16x16x32_bf16 v[24:27], v[68:71], v[202:205], v[24:27]
	v_mfma_f32_16x16x32_bf16 v[12:15], v[60:63], v[242:245], v[12:15]
	v_mfma_f32_16x16x32_bf16 v[8:11], v[68:71], v[242:245], v[8:11]
	v_mfma_f32_16x16x32_bf16 v[48:51], v[72:75], v[80:83], v[48:51]
	v_mfma_f32_16x16x32_bf16 v[84:87], v[76:79], v[182:185], v[48:51]
	v_mfma_f32_16x16x32_bf16 v[48:51], v[170:173], v[80:83], v[52:55]
	v_mfma_f32_16x16x32_bf16 v[36:39], v[72:75], v[186:189], v[36:39]
	v_mfma_f32_16x16x32_bf16 v[32:35], v[170:173], v[186:189], v[32:35]
	v_mfma_f32_16x16x32_bf16 v[20:23], v[72:75], v[198:201], v[20:23]
	v_mfma_f32_16x16x32_bf16 v[16:19], v[170:173], v[198:201], v[16:19]
	v_mfma_f32_16x16x32_bf16 v[4:7], v[72:75], v[212:215], v[4:7]
	v_mfma_f32_16x16x32_bf16 v[0:3], v[170:173], v[212:215], v[0:3]
	v_mfma_f32_16x16x32_bf16 v[80:83], v[178:181], v[182:185], v[48:51]
	v_mfma_f32_16x16x32_bf16 v[36:39], v[76:79], v[194:197], v[36:39]
	v_mfma_f32_16x16x32_bf16 v[32:35], v[178:181], v[194:197], v[32:35]
	v_mfma_f32_16x16x32_bf16 v[20:23], v[76:79], v[202:205], v[20:23]
	v_mfma_f32_16x16x32_bf16 v[16:19], v[178:181], v[202:205], v[16:19]
	v_mfma_f32_16x16x32_bf16 v[4:7], v[76:79], v[242:245], v[4:7]
	v_mfma_f32_16x16x32_bf16 v[0:3], v[178:181], v[242:245], v[0:3]
	s_setprio 0
	s_barrier
	s_add_u32 s28, s28, 0x100
	s_addc_u32 s29, s29, 0
	s_add_u32 s18, s18, 0x100
	s_addc_u32 s19, s19, 0
	s_cmp_ge_u32 s21, s11
	s_mov_b32 s20, s21
	s_cbranch_scc0 .LBB0_92

.LBB0_113:
	s_add_i32 s21, s20, 2
	s_add_u32 s12, s28, 0x80
	s_addc_u32 s13, s29, 0
	s_add_i32 s36, 0, 0x10000
	s_cmp_eq_u32 s85, s20
	s_cselect_b32 s59, s5, s13
	s_cselect_b32 s58, s4, s12
	v_add_u32_e32 v142, s36, v145
	s_cselect_b32 s13, s57, s19
	s_cselect_b32 s12, s56, s18
	s_add_i32 s20, 0, 0x14000
	ds_read_b128 v[138:141], v142
	ds_read_b128 v[148:151], v142 offset:1024
	ds_read_b128 v[152:155], v142 offset:2048
	ds_read_b128 v[156:159], v142 offset:3072
	v_add_u32_e32 v142, s20, v145
	ds_read_b128 v[160:163], v142
	ds_read_b128 v[164:167], v142 offset:1024
	ds_read_b128 v[168:171], v142 offset:2048
	ds_read_b128 v[172:175], v142 offset:3072
	s_add_i32 m0, s77, 0xc000
	ds_read_b128 v[176:179], v147
	ds_read_b128 v[180:183], v147 offset:1024
	ds_read_b128 v[184:187], v147 offset:2048
	ds_read_b128 v[188:191], v147 offset:3072
	ds_read_b128 v[194:197], v147 offset:4096
	ds_read_b128 v[198:201], v147 offset:5120
	ds_read_b128 v[202:205], v147 offset:6144
	ds_read_b128 v[212:215], v147 offset:7168
	global_load_lds_dwordx4 v134, s[28:29]
	s_add_i32 m0, s77, 0xe000
	s_nop 0
	global_load_lds_dwordx4 v136, s[28:29]
	s_waitcnt vmcnt(8)
	s_waitcnt lgkmcnt(0)
	s_barrier
	s_setprio 1
	v_mfma_f32_16x16x32_bf16 v[124:127], v[138:141], v[176:179], v[124:127]
	v_mfma_f32_16x16x32_bf16 v[120:123], v[152:155], v[176:179], v[120:123]
	v_mfma_f32_16x16x32_bf16 v[108:111], v[138:141], v[184:187], v[108:111]
	v_mfma_f32_16x16x32_bf16 v[104:107], v[152:155], v[184:187], v[104:107]
	v_mfma_f32_16x16x32_bf16 v[92:95], v[138:141], v[194:197], v[92:95]
	v_mfma_f32_16x16x32_bf16 v[88:91], v[152:155], v[194:197], v[88:91]
	v_mfma_f32_16x16x32_bf16 v[76:79], v[138:141], v[202:205], v[76:79]
	v_mfma_f32_16x16x32_bf16 v[72:75], v[152:155], v[202:205], v[72:75]
	v_mfma_f32_16x16x32_bf16 v[124:127], v[148:151], v[180:183], v[124:127]
	v_mfma_f32_16x16x32_bf16 v[120:123], v[156:159], v[180:183], v[120:123]
	v_mfma_f32_16x16x32_bf16 v[108:111], v[148:151], v[188:191], v[108:111]
	v_mfma_f32_16x16x32_bf16 v[104:107], v[156:159], v[188:191], v[104:107]
	v_mfma_f32_16x16x32_bf16 v[92:95], v[148:151], v[198:201], v[92:95]
	v_mfma_f32_16x16x32_bf16 v[88:91], v[156:159], v[198:201], v[88:91]
	v_mfma_f32_16x16x32_bf16 v[76:79], v[148:151], v[212:215], v[76:79]
	v_mfma_f32_16x16x32_bf16 v[72:75], v[156:159], v[212:215], v[72:75]
	v_mfma_f32_16x16x32_bf16 v[116:119], v[160:163], v[176:179], v[116:119]
	v_mfma_f32_16x16x32_bf16 v[112:115], v[168:171], v[176:179], v[112:115]
	v_mfma_f32_16x16x32_bf16 v[100:103], v[160:163], v[184:187], v[100:103]
	v_mfma_f32_16x16x32_bf16 v[96:99], v[168:171], v[184:187], v[96:99]
	v_mfma_f32_16x16x32_bf16 v[84:87], v[160:163], v[194:197], v[84:87]
	v_mfma_f32_16x16x32_bf16 v[80:83], v[168:171], v[194:197], v[80:83]
	v_mfma_f32_16x16x32_bf16 v[68:71], v[160:163], v[202:205], v[68:71]
	v_mfma_f32_16x16x32_bf16 v[64:67], v[168:171], v[202:205], v[64:67]
	v_mfma_f32_16x16x32_bf16 v[116:119], v[164:167], v[180:183], v[116:119]
	v_mfma_f32_16x16x32_bf16 v[112:115], v[172:175], v[180:183], v[112:115]
	v_mfma_f32_16x16x32_bf16 v[100:103], v[164:167], v[188:191], v[100:103]
	v_mfma_f32_16x16x32_bf16 v[96:99], v[172:175], v[188:191], v[96:99]
	v_mfma_f32_16x16x32_bf16 v[84:87], v[164:167], v[198:201], v[84:87]
	v_mfma_f32_16x16x32_bf16 v[80:83], v[172:175], v[198:201], v[80:83]
	v_mfma_f32_16x16x32_bf16 v[68:71], v[164:167], v[212:215], v[68:71]
	v_mfma_f32_16x16x32_bf16 v[64:67], v[172:175], v[212:215], v[64:67]
	s_setprio 0
	s_barrier
	s_add_i32 s36, s36, s71
	s_mov_b64 vcc, s[12:13]
	s_mov_b32 m0, s36
	ds_read_b128 v[176:179], v147 offset:16384
	ds_read_b128 v[180:183], v147 offset:17408
	ds_read_b128 v[184:187], v147 offset:18432
	ds_read_b128 v[188:191], v147 offset:19456
	ds_read_b128 v[194:197], v147 offset:20480
	ds_read_b128 v[198:201], v147 offset:21504
	ds_read_b128 v[202:205], v147 offset:22528
	ds_read_b128 v[212:215], v147 offset:23552
	global_load_lds_dwordx4 v192, s[12:13]
	s_add_i32 m0, s36, 0x2000
	s_add_i32 s20, s20, s71
	global_load_lds_dwordx4 v128, s[12:13]
	s_add_u32 s12, s12, s9
	s_addc_u32 s13, s13, 0
	s_mov_b32 m0, s20
	s_nop 0
	global_load_lds_dwordx4 v192, s[12:13]
	s_add_i32 m0, s20, 0x2000
	s_nop 0
	global_load_lds_dwordx4 v128, s[12:13]
	s_mov_b32 m0, s77
	s_nop 0
	global_load_lds_dwordx4 v132, s[58:59]
	s_mov_b32 m0, s78
	s_nop 0
	global_load_lds_dwordx4 v130, s[58:59]
	s_waitcnt vmcnt(8)
	s_waitcnt lgkmcnt(0)
	s_barrier
	s_setprio 1
	v_mfma_f32_16x16x32_bf16 v[60:63], v[138:141], v[176:179], v[60:63]
	v_mfma_f32_16x16x32_bf16 v[56:59], v[152:155], v[176:179], v[56:59]
	v_mfma_f32_16x16x32_bf16 v[44:47], v[138:141], v[184:187], v[44:47]
	v_mfma_f32_16x16x32_bf16 v[40:43], v[152:155], v[184:187], v[40:43]
	v_mfma_f32_16x16x32_bf16 v[28:31], v[138:141], v[194:197], v[28:31]
	v_mfma_f32_16x16x32_bf16 v[24:27], v[152:155], v[194:197], v[24:27]
	v_mfma_f32_16x16x32_bf16 v[12:15], v[138:141], v[202:205], v[12:15]
	v_mfma_f32_16x16x32_bf16 v[8:11], v[152:155], v[202:205], v[8:11]
	v_mfma_f32_16x16x32_bf16 v[60:63], v[148:151], v[180:183], v[60:63]
	v_mfma_f32_16x16x32_bf16 v[56:59], v[156:159], v[180:183], v[56:59]
	v_mfma_f32_16x16x32_bf16 v[44:47], v[148:151], v[188:191], v[44:47]
	v_mfma_f32_16x16x32_bf16 v[40:43], v[156:159], v[188:191], v[40:43]
	v_mfma_f32_16x16x32_bf16 v[28:31], v[148:151], v[198:201], v[28:31]
	v_mfma_f32_16x16x32_bf16 v[24:27], v[156:159], v[198:201], v[24:27]
	v_mfma_f32_16x16x32_bf16 v[12:15], v[148:151], v[212:215], v[12:15]
	v_mfma_f32_16x16x32_bf16 v[8:11], v[156:159], v[212:215], v[8:11]
	v_mfma_f32_16x16x32_bf16 v[52:55], v[160:163], v[176:179], v[52:55]
	v_mfma_f32_16x16x32_bf16 v[48:51], v[168:171], v[176:179], v[48:51]
	v_mfma_f32_16x16x32_bf16 v[36:39], v[160:163], v[184:187], v[36:39]
	v_mfma_f32_16x16x32_bf16 v[32:35], v[168:171], v[184:187], v[32:35]
	v_mfma_f32_16x16x32_bf16 v[20:23], v[160:163], v[194:197], v[20:23]
	v_mfma_f32_16x16x32_bf16 v[16:19], v[168:171], v[194:197], v[16:19]
	v_mfma_f32_16x16x32_bf16 v[4:7], v[160:163], v[202:205], v[4:7]
	v_mfma_f32_16x16x32_bf16 v[0:3], v[168:171], v[202:205], v[0:3]
	v_mfma_f32_16x16x32_bf16 v[52:55], v[164:167], v[180:183], v[52:55]
	v_mfma_f32_16x16x32_bf16 v[48:51], v[172:175], v[180:183], v[48:51]
	v_mfma_f32_16x16x32_bf16 v[36:39], v[164:167], v[188:191], v[36:39]
	v_mfma_f32_16x16x32_bf16 v[32:35], v[172:175], v[188:191], v[32:35]
	v_mfma_f32_16x16x32_bf16 v[20:23], v[164:167], v[198:201], v[20:23]
	v_mfma_f32_16x16x32_bf16 v[16:19], v[172:175], v[198:201], v[16:19]
	v_mfma_f32_16x16x32_bf16 v[4:7], v[164:167], v[212:215], v[4:7]
	v_mfma_f32_16x16x32_bf16 v[0:3], v[172:175], v[212:215], v[0:3]
	s_setprio 0
	s_barrier
	s_add_i32 s20, 0, 0x18000
	s_add_i32 s36, 0, 0x1c000
	v_add_u32_e32 v156, s20, v145
	v_add_u32_e32 v172, s36, v145
	ds_read_b128 v[138:141], v156
	ds_read_b128 v[148:151], v156 offset:1024
	ds_read_b128 v[152:155], v156 offset:2048
	ds_read_b128 v[156:159], v156 offset:3072
	ds_read_b128 v[160:163], v172
	ds_read_b128 v[164:167], v172 offset:1024
	ds_read_b128 v[168:171], v172 offset:2048
	ds_read_b128 v[172:175], v172 offset:3072
	s_add_u32 s12, s58, s34
	s_addc_u32 s13, s59, 0
	s_mov_b32 m0, s79
	ds_read_b128 v[176:179], v147 offset:32768
	ds_read_b128 v[180:183], v147 offset:33792
	ds_read_b128 v[184:187], v147 offset:34816
	ds_read_b128 v[188:191], v147 offset:35840
	ds_read_b128 v[194:197], v147 offset:36864
	ds_read_b128 v[198:201], v147 offset:37888
	ds_read_b128 v[202:205], v147 offset:38912
	ds_read_b128 v[212:215], v147 offset:39936
	global_load_lds_dwordx4 v132, s[12:13]
	s_mov_b32 m0, s80
	s_nop 0
	global_load_lds_dwordx4 v130, s[12:13]
	s_waitcnt vmcnt(8)
	s_waitcnt lgkmcnt(0)
	s_barrier
	s_setprio 1
	v_mfma_f32_16x16x32_bf16 v[124:127], v[138:141], v[176:179], v[124:127]
	v_mfma_f32_16x16x32_bf16 v[120:123], v[152:155], v[176:179], v[120:123]
	v_mfma_f32_16x16x32_bf16 v[108:111], v[138:141], v[184:187], v[108:111]
	v_mfma_f32_16x16x32_bf16 v[104:107], v[152:155], v[184:187], v[104:107]
	v_mfma_f32_16x16x32_bf16 v[92:95], v[138:141], v[194:197], v[92:95]
	v_mfma_f32_16x16x32_bf16 v[88:91], v[152:155], v[194:197], v[88:91]
	v_mfma_f32_16x16x32_bf16 v[76:79], v[138:141], v[202:205], v[76:79]
	v_mfma_f32_16x16x32_bf16 v[72:75], v[152:155], v[202:205], v[72:75]
	v_mfma_f32_16x16x32_bf16 v[124:127], v[148:151], v[180:183], v[124:127]
	v_mfma_f32_16x16x32_bf16 v[120:123], v[156:159], v[180:183], v[120:123]
	v_mfma_f32_16x16x32_bf16 v[108:111], v[148:151], v[188:191], v[108:111]
	v_mfma_f32_16x16x32_bf16 v[104:107], v[156:159], v[188:191], v[104:107]
	v_mfma_f32_16x16x32_bf16 v[92:95], v[148:151], v[198:201], v[92:95]
	v_mfma_f32_16x16x32_bf16 v[88:91], v[156:159], v[198:201], v[88:91]
	v_mfma_f32_16x16x32_bf16 v[76:79], v[148:151], v[212:215], v[76:79]
	v_mfma_f32_16x16x32_bf16 v[72:75], v[156:159], v[212:215], v[72:75]
	v_mfma_f32_16x16x32_bf16 v[116:119], v[160:163], v[176:179], v[116:119]
	v_mfma_f32_16x16x32_bf16 v[112:115], v[168:171], v[176:179], v[112:115]
	v_mfma_f32_16x16x32_bf16 v[100:103], v[160:163], v[184:187], v[100:103]
	v_mfma_f32_16x16x32_bf16 v[96:99], v[168:171], v[184:187], v[96:99]
	v_mfma_f32_16x16x32_bf16 v[84:87], v[160:163], v[194:197], v[84:87]
	v_mfma_f32_16x16x32_bf16 v[80:83], v[168:171], v[194:197], v[80:83]
	v_mfma_f32_16x16x32_bf16 v[68:71], v[160:163], v[202:205], v[68:71]
	v_mfma_f32_16x16x32_bf16 v[64:67], v[168:171], v[202:205], v[64:67]
	v_mfma_f32_16x16x32_bf16 v[116:119], v[164:167], v[180:183], v[116:119]
	v_mfma_f32_16x16x32_bf16 v[112:115], v[172:175], v[180:183], v[112:115]
	v_mfma_f32_16x16x32_bf16 v[100:103], v[164:167], v[188:191], v[100:103]
	v_mfma_f32_16x16x32_bf16 v[96:99], v[172:175], v[188:191], v[96:99]
	v_mfma_f32_16x16x32_bf16 v[84:87], v[164:167], v[198:201], v[84:87]
	v_mfma_f32_16x16x32_bf16 v[80:83], v[172:175], v[198:201], v[80:83]
	v_mfma_f32_16x16x32_bf16 v[68:71], v[164:167], v[212:215], v[68:71]
	v_mfma_f32_16x16x32_bf16 v[64:67], v[172:175], v[212:215], v[64:67]
	s_setprio 0
	s_barrier
	s_add_i32 m0, s20, s71
	s_add_u32 s12, vcc_lo, 0x80
	s_addc_u32 s13, vcc_hi, 0
	ds_read_b128 v[176:179], v147 offset:49152
	ds_read_b128 v[180:183], v147 offset:50176
	ds_read_b128 v[184:187], v147 offset:51200
	ds_read_b128 v[188:191], v147 offset:52224
	ds_read_b128 v[194:197], v147 offset:53248
	ds_read_b128 v[198:201], v147 offset:54272
	ds_read_b128 v[202:205], v147 offset:55296
	ds_read_b128 v[212:215], v147 offset:56320
	global_load_lds_dwordx4 v192, s[12:13]
	s_add_i32 m0, m0, 0x2000
	s_nop 0
	global_load_lds_dwordx4 v128, s[12:13]
	s_add_u32 s12, s12, s9
	s_addc_u32 s13, s13, 0
	s_add_i32 m0, s36, s71
	s_nop 0
	global_load_lds_dwordx4 v192, s[12:13]
	s_add_i32 m0, m0, 0x2000
	s_nop 0
	global_load_lds_dwordx4 v128, s[12:13]
	s_add_u32 s12, s58, 0x80
	s_addc_u32 s13, s59, 0
	s_mov_b32 m0, s81
	s_nop 0
	global_load_lds_dwordx4 v132, s[12:13]
	s_mov_b32 m0, s82
	s_nop 0
	global_load_lds_dwordx4 v130, s[12:13]
	s_waitcnt vmcnt(8)
	s_waitcnt lgkmcnt(0)
	s_barrier
	s_setprio 1
	v_mfma_f32_16x16x32_bf16 v[60:63], v[138:141], v[176:179], v[60:63]
	v_mfma_f32_16x16x32_bf16 v[56:59], v[152:155], v[176:179], v[56:59]
	v_mfma_f32_16x16x32_bf16 v[44:47], v[138:141], v[184:187], v[44:47]
	v_mfma_f32_16x16x32_bf16 v[40:43], v[152:155], v[184:187], v[40:43]
	v_mfma_f32_16x16x32_bf16 v[28:31], v[138:141], v[194:197], v[28:31]
	v_mfma_f32_16x16x32_bf16 v[24:27], v[152:155], v[194:197], v[24:27]
	v_mfma_f32_16x16x32_bf16 v[12:15], v[138:141], v[202:205], v[12:15]
	v_mfma_f32_16x16x32_bf16 v[8:11], v[152:155], v[202:205], v[8:11]
	v_mfma_f32_16x16x32_bf16 v[60:63], v[148:151], v[180:183], v[60:63]
	v_mfma_f32_16x16x32_bf16 v[56:59], v[156:159], v[180:183], v[56:59]
	v_mfma_f32_16x16x32_bf16 v[44:47], v[148:151], v[188:191], v[44:47]
	v_mfma_f32_16x16x32_bf16 v[40:43], v[156:159], v[188:191], v[40:43]
	v_mfma_f32_16x16x32_bf16 v[28:31], v[148:151], v[198:201], v[28:31]
	v_mfma_f32_16x16x32_bf16 v[24:27], v[156:159], v[198:201], v[24:27]
	v_mfma_f32_16x16x32_bf16 v[12:15], v[148:151], v[212:215], v[12:15]
	v_mfma_f32_16x16x32_bf16 v[8:11], v[156:159], v[212:215], v[8:11]
	v_mfma_f32_16x16x32_bf16 v[52:55], v[160:163], v[176:179], v[52:55]
	v_mfma_f32_16x16x32_bf16 v[48:51], v[168:171], v[176:179], v[48:51]
	v_mfma_f32_16x16x32_bf16 v[36:39], v[160:163], v[184:187], v[36:39]
	v_mfma_f32_16x16x32_bf16 v[32:35], v[168:171], v[184:187], v[32:35]
	v_mfma_f32_16x16x32_bf16 v[20:23], v[160:163], v[194:197], v[20:23]
	v_mfma_f32_16x16x32_bf16 v[16:19], v[168:171], v[194:197], v[16:19]
	v_mfma_f32_16x16x32_bf16 v[4:7], v[160:163], v[202:205], v[4:7]
	v_mfma_f32_16x16x32_bf16 v[0:3], v[168:171], v[202:205], v[0:3]
	v_mfma_f32_16x16x32_bf16 v[52:55], v[164:167], v[180:183], v[52:55]
	v_mfma_f32_16x16x32_bf16 v[48:51], v[172:175], v[180:183], v[48:51]
	v_mfma_f32_16x16x32_bf16 v[36:39], v[164:167], v[188:191], v[36:39]
	v_mfma_f32_16x16x32_bf16 v[32:35], v[172:175], v[188:191], v[32:35]
	v_mfma_f32_16x16x32_bf16 v[20:23], v[164:167], v[198:201], v[20:23]
	v_mfma_f32_16x16x32_bf16 v[16:19], v[172:175], v[198:201], v[16:19]
	v_mfma_f32_16x16x32_bf16 v[4:7], v[164:167], v[212:215], v[4:7]
	v_mfma_f32_16x16x32_bf16 v[0:3], v[172:175], v[212:215], v[0:3]
	s_setprio 0
	s_barrier
	s_add_u32 s28, s28, 0x100
	s_addc_u32 s29, s29, 0
	s_add_u32 s18, s18, 0x100
	s_addc_u32 s19, s19, 0
	s_cmp_ge_u32 s21, s83
	s_mov_b32 s20, s21
	s_cbranch_scc0 .LBB0_113
	s_and_b64 vcc, exec, s[54:55]
	s_cbranch_vccz .LBB0_116

.LBB0_137:
	s_add_i32 s21, s20, 2
	s_add_u32 s12, s28, 0x80
	s_addc_u32 s13, s29, 0
	s_add_i32 s36, 0, 0x10000
	s_cmp_eq_u32 s81, s20
	s_cselect_b32 s55, s5, s13
	s_cselect_b32 s54, s4, s12
	s_cselect_b32 s13, s53, s19
	s_cselect_b32 s12, s52, s18
	s_add_i32 s20, 0, 0x14000
	v_add_u32_e32 v154, s36, v139
	v_add_u32_e32 v170, s20, v139
	ds_read_b128 v[142:145], v154
	ds_read_b128 v[146:149], v154 offset:1024
	ds_read_b128 v[150:153], v154 offset:2048
	ds_read_b128 v[154:157], v154 offset:3072
	ds_read_b128 v[158:161], v170
	ds_read_b128 v[162:165], v170 offset:1024
	ds_read_b128 v[166:169], v170 offset:2048
	ds_read_b128 v[170:173], v170 offset:3072
	s_add_i32 m0, s73, 0xc000
	ds_read_b128 v[174:177], v141
	ds_read_b128 v[178:181], v141 offset:1024
	ds_read_b128 v[182:185], v141 offset:2048
	ds_read_b128 v[186:189], v141 offset:3072
	ds_read_b128 v[194:197], v141 offset:4096
	ds_read_b128 v[198:201], v141 offset:5120
	ds_read_b128 v[202:205], v141 offset:6144
	ds_read_b128 v[212:215], v141 offset:7168
	global_load_lds_dwordx4 v134, s[28:29]
	s_add_i32 m0, s73, 0xe000
	s_nop 0
	global_load_lds_dwordx4 v136, s[28:29]
	s_waitcnt vmcnt(8)
	s_waitcnt lgkmcnt(0)
	s_barrier
	s_setprio 1
	v_mfma_f32_16x16x32_bf16 v[124:127], v[142:145], v[174:177], v[124:127]
	v_mfma_f32_16x16x32_bf16 v[116:119], v[150:153], v[174:177], v[116:119]
	v_mfma_f32_16x16x32_bf16 v[108:111], v[142:145], v[182:185], v[108:111]
	v_mfma_f32_16x16x32_bf16 v[100:103], v[150:153], v[182:185], v[100:103]
	v_mfma_f32_16x16x32_bf16 v[92:95], v[142:145], v[194:197], v[92:95]
	v_mfma_f32_16x16x32_bf16 v[84:87], v[150:153], v[194:197], v[84:87]
	v_mfma_f32_16x16x32_bf16 v[76:79], v[142:145], v[202:205], v[76:79]
	v_mfma_f32_16x16x32_bf16 v[68:71], v[150:153], v[202:205], v[68:71]
	v_mfma_f32_16x16x32_bf16 v[124:127], v[146:149], v[178:181], v[124:127]
	v_mfma_f32_16x16x32_bf16 v[116:119], v[154:157], v[178:181], v[116:119]
	v_mfma_f32_16x16x32_bf16 v[108:111], v[146:149], v[186:189], v[108:111]
	v_mfma_f32_16x16x32_bf16 v[100:103], v[154:157], v[186:189], v[100:103]
	v_mfma_f32_16x16x32_bf16 v[92:95], v[146:149], v[198:201], v[92:95]
	v_mfma_f32_16x16x32_bf16 v[84:87], v[154:157], v[198:201], v[84:87]
	v_mfma_f32_16x16x32_bf16 v[76:79], v[146:149], v[212:215], v[76:79]
	v_mfma_f32_16x16x32_bf16 v[68:71], v[154:157], v[212:215], v[68:71]
	v_mfma_f32_16x16x32_bf16 v[120:123], v[158:161], v[174:177], v[120:123]
	v_mfma_f32_16x16x32_bf16 v[112:115], v[166:169], v[174:177], v[112:115]
	v_mfma_f32_16x16x32_bf16 v[104:107], v[158:161], v[182:185], v[104:107]
	v_mfma_f32_16x16x32_bf16 v[96:99], v[166:169], v[182:185], v[96:99]
	v_mfma_f32_16x16x32_bf16 v[88:91], v[158:161], v[194:197], v[88:91]
	v_mfma_f32_16x16x32_bf16 v[80:83], v[166:169], v[194:197], v[80:83]
	v_mfma_f32_16x16x32_bf16 v[72:75], v[158:161], v[202:205], v[72:75]
	v_mfma_f32_16x16x32_bf16 v[64:67], v[166:169], v[202:205], v[64:67]
	v_mfma_f32_16x16x32_bf16 v[120:123], v[162:165], v[178:181], v[120:123]
	v_mfma_f32_16x16x32_bf16 v[112:115], v[170:173], v[178:181], v[112:115]
	v_mfma_f32_16x16x32_bf16 v[104:107], v[162:165], v[186:189], v[104:107]
	v_mfma_f32_16x16x32_bf16 v[96:99], v[170:173], v[186:189], v[96:99]
	v_mfma_f32_16x16x32_bf16 v[88:91], v[162:165], v[198:201], v[88:91]
	v_mfma_f32_16x16x32_bf16 v[80:83], v[170:173], v[198:201], v[80:83]
	v_mfma_f32_16x16x32_bf16 v[72:75], v[162:165], v[212:215], v[72:75]
	v_mfma_f32_16x16x32_bf16 v[64:67], v[170:173], v[212:215], v[64:67]
	s_setprio 0
	s_barrier
	s_add_i32 s36, s36, s57
	s_mov_b64 vcc, s[12:13]
	s_mov_b32 m0, s36
	ds_read_b128 v[174:177], v141 offset:16384
	ds_read_b128 v[178:181], v141 offset:17408
	ds_read_b128 v[182:185], v141 offset:18432
	ds_read_b128 v[186:189], v141 offset:19456
	ds_read_b128 v[194:197], v141 offset:20480
	ds_read_b128 v[198:201], v141 offset:21504
	ds_read_b128 v[202:205], v141 offset:22528
	ds_read_b128 v[212:215], v141 offset:23552
	global_load_lds_dwordx4 v192, s[12:13]
	s_add_i32 m0, s36, 0x2000
	s_add_i32 s20, s20, s57
	global_load_lds_dwordx4 v128, s[12:13]
	s_add_u32 s12, s12, s9
	s_addc_u32 s13, s13, 0
	s_mov_b32 m0, s20
	s_nop 0
	global_load_lds_dwordx4 v192, s[12:13]
	s_add_i32 m0, s20, 0x2000
	s_nop 0
	global_load_lds_dwordx4 v128, s[12:13]
	s_mov_b32 m0, s73
	s_nop 0
	global_load_lds_dwordx4 v132, s[54:55]
	s_mov_b32 m0, s74
	s_nop 0
	global_load_lds_dwordx4 v130, s[54:55]
	s_waitcnt vmcnt(8)
	s_waitcnt lgkmcnt(0)
	s_barrier
	s_setprio 1
	v_mfma_f32_16x16x32_bf16 v[60:63], v[142:145], v[174:177], v[60:63]
	v_mfma_f32_16x16x32_bf16 v[52:55], v[150:153], v[174:177], v[52:55]
	v_mfma_f32_16x16x32_bf16 v[44:47], v[142:145], v[182:185], v[44:47]
	v_mfma_f32_16x16x32_bf16 v[36:39], v[150:153], v[182:185], v[36:39]
	v_mfma_f32_16x16x32_bf16 v[28:31], v[142:145], v[194:197], v[28:31]
	v_mfma_f32_16x16x32_bf16 v[20:23], v[150:153], v[194:197], v[20:23]
	v_mfma_f32_16x16x32_bf16 v[12:15], v[142:145], v[202:205], v[12:15]
	v_mfma_f32_16x16x32_bf16 v[4:7], v[150:153], v[202:205], v[4:7]
	v_mfma_f32_16x16x32_bf16 v[60:63], v[146:149], v[178:181], v[60:63]
	v_mfma_f32_16x16x32_bf16 v[52:55], v[154:157], v[178:181], v[52:55]
	v_mfma_f32_16x16x32_bf16 v[44:47], v[146:149], v[186:189], v[44:47]
	v_mfma_f32_16x16x32_bf16 v[36:39], v[154:157], v[186:189], v[36:39]
	v_mfma_f32_16x16x32_bf16 v[28:31], v[146:149], v[198:201], v[28:31]
	v_mfma_f32_16x16x32_bf16 v[20:23], v[154:157], v[198:201], v[20:23]
	v_mfma_f32_16x16x32_bf16 v[12:15], v[146:149], v[212:215], v[12:15]
	v_mfma_f32_16x16x32_bf16 v[4:7], v[154:157], v[212:215], v[4:7]
	v_mfma_f32_16x16x32_bf16 v[56:59], v[158:161], v[174:177], v[56:59]
	v_mfma_f32_16x16x32_bf16 v[48:51], v[166:169], v[174:177], v[48:51]
	v_mfma_f32_16x16x32_bf16 v[40:43], v[158:161], v[182:185], v[40:43]
	v_mfma_f32_16x16x32_bf16 v[32:35], v[166:169], v[182:185], v[32:35]
	v_mfma_f32_16x16x32_bf16 v[24:27], v[158:161], v[194:197], v[24:27]
	v_mfma_f32_16x16x32_bf16 v[16:19], v[166:169], v[194:197], v[16:19]
	v_mfma_f32_16x16x32_bf16 v[8:11], v[158:161], v[202:205], v[8:11]
	v_mfma_f32_16x16x32_bf16 v[0:3], v[166:169], v[202:205], v[0:3]
	v_mfma_f32_16x16x32_bf16 v[56:59], v[162:165], v[178:181], v[56:59]
	v_mfma_f32_16x16x32_bf16 v[48:51], v[170:173], v[178:181], v[48:51]
	v_mfma_f32_16x16x32_bf16 v[40:43], v[162:165], v[186:189], v[40:43]
	v_mfma_f32_16x16x32_bf16 v[32:35], v[170:173], v[186:189], v[32:35]
	v_mfma_f32_16x16x32_bf16 v[24:27], v[162:165], v[198:201], v[24:27]
	v_mfma_f32_16x16x32_bf16 v[16:19], v[170:173], v[198:201], v[16:19]
	v_mfma_f32_16x16x32_bf16 v[8:11], v[162:165], v[212:215], v[8:11]
	v_mfma_f32_16x16x32_bf16 v[0:3], v[170:173], v[212:215], v[0:3]
	s_setprio 0
	s_barrier
	s_add_i32 s20, 0, 0x18000
	s_add_i32 s36, 0, 0x1c000
	v_add_u32_e32 v154, s20, v139
	v_add_u32_e32 v170, s36, v139
	ds_read_b128 v[142:145], v154
	ds_read_b128 v[146:149], v154 offset:1024
	ds_read_b128 v[150:153], v154 offset:2048
	ds_read_b128 v[154:157], v154 offset:3072
	ds_read_b128 v[158:161], v170
	ds_read_b128 v[162:165], v170 offset:1024
	ds_read_b128 v[166:169], v170 offset:2048
	ds_read_b128 v[170:173], v170 offset:3072
	s_add_u32 s12, s54, s34
	s_addc_u32 s13, s55, 0
	s_mov_b32 m0, s75
	ds_read_b128 v[174:177], v141 offset:32768
	ds_read_b128 v[178:181], v141 offset:33792
	ds_read_b128 v[182:185], v141 offset:34816
	ds_read_b128 v[186:189], v141 offset:35840
	ds_read_b128 v[194:197], v141 offset:36864
	ds_read_b128 v[198:201], v141 offset:37888
	ds_read_b128 v[202:205], v141 offset:38912
	ds_read_b128 v[212:215], v141 offset:39936
	global_load_lds_dwordx4 v132, s[12:13]
	s_mov_b32 m0, s76
	s_nop 0
	global_load_lds_dwordx4 v130, s[12:13]
	s_waitcnt vmcnt(8)
	s_waitcnt lgkmcnt(0)
	s_barrier
	s_setprio 1
	v_mfma_f32_16x16x32_bf16 v[124:127], v[142:145], v[174:177], v[124:127]
	v_mfma_f32_16x16x32_bf16 v[116:119], v[150:153], v[174:177], v[116:119]
	v_mfma_f32_16x16x32_bf16 v[108:111], v[142:145], v[182:185], v[108:111]
	v_mfma_f32_16x16x32_bf16 v[100:103], v[150:153], v[182:185], v[100:103]
	v_mfma_f32_16x16x32_bf16 v[92:95], v[142:145], v[194:197], v[92:95]
	v_mfma_f32_16x16x32_bf16 v[84:87], v[150:153], v[194:197], v[84:87]
	v_mfma_f32_16x16x32_bf16 v[76:79], v[142:145], v[202:205], v[76:79]
	v_mfma_f32_16x16x32_bf16 v[68:71], v[150:153], v[202:205], v[68:71]
	v_mfma_f32_16x16x32_bf16 v[124:127], v[146:149], v[178:181], v[124:127]
	v_mfma_f32_16x16x32_bf16 v[116:119], v[154:157], v[178:181], v[116:119]
	v_mfma_f32_16x16x32_bf16 v[108:111], v[146:149], v[186:189], v[108:111]
	v_mfma_f32_16x16x32_bf16 v[100:103], v[154:157], v[186:189], v[100:103]
	v_mfma_f32_16x16x32_bf16 v[92:95], v[146:149], v[198:201], v[92:95]
	v_mfma_f32_16x16x32_bf16 v[84:87], v[154:157], v[198:201], v[84:87]
	v_mfma_f32_16x16x32_bf16 v[76:79], v[146:149], v[212:215], v[76:79]
	v_mfma_f32_16x16x32_bf16 v[68:71], v[154:157], v[212:215], v[68:71]
	v_mfma_f32_16x16x32_bf16 v[120:123], v[158:161], v[174:177], v[120:123]
	v_mfma_f32_16x16x32_bf16 v[112:115], v[166:169], v[174:177], v[112:115]
	v_mfma_f32_16x16x32_bf16 v[104:107], v[158:161], v[182:185], v[104:107]
	v_mfma_f32_16x16x32_bf16 v[96:99], v[166:169], v[182:185], v[96:99]
	v_mfma_f32_16x16x32_bf16 v[88:91], v[158:161], v[194:197], v[88:91]
	v_mfma_f32_16x16x32_bf16 v[80:83], v[166:169], v[194:197], v[80:83]
	v_mfma_f32_16x16x32_bf16 v[72:75], v[158:161], v[202:205], v[72:75]
	v_mfma_f32_16x16x32_bf16 v[64:67], v[166:169], v[202:205], v[64:67]
	v_mfma_f32_16x16x32_bf16 v[120:123], v[162:165], v[178:181], v[120:123]
	v_mfma_f32_16x16x32_bf16 v[112:115], v[170:173], v[178:181], v[112:115]
	v_mfma_f32_16x16x32_bf16 v[104:107], v[162:165], v[186:189], v[104:107]
	v_mfma_f32_16x16x32_bf16 v[96:99], v[170:173], v[186:189], v[96:99]
	v_mfma_f32_16x16x32_bf16 v[88:91], v[162:165], v[198:201], v[88:91]
	v_mfma_f32_16x16x32_bf16 v[80:83], v[170:173], v[198:201], v[80:83]
	v_mfma_f32_16x16x32_bf16 v[72:75], v[162:165], v[212:215], v[72:75]
	v_mfma_f32_16x16x32_bf16 v[64:67], v[170:173], v[212:215], v[64:67]
	s_setprio 0
	s_barrier
	s_add_i32 m0, s20, s57
	s_add_u32 s12, vcc_lo, 0x80
	s_addc_u32 s13, vcc_hi, 0
	ds_read_b128 v[174:177], v141 offset:49152
	ds_read_b128 v[178:181], v141 offset:50176
	ds_read_b128 v[182:185], v141 offset:51200
	ds_read_b128 v[186:189], v141 offset:52224
	ds_read_b128 v[194:197], v141 offset:53248
	ds_read_b128 v[198:201], v141 offset:54272
	ds_read_b128 v[202:205], v141 offset:55296
	ds_read_b128 v[212:215], v141 offset:56320
	global_load_lds_dwordx4 v192, s[12:13]
	s_add_i32 m0, m0, 0x2000
	s_nop 0
	global_load_lds_dwordx4 v128, s[12:13]
	s_add_u32 s12, s12, s9
	s_addc_u32 s13, s13, 0
	s_add_i32 m0, s36, s57
	s_nop 0
	global_load_lds_dwordx4 v192, s[12:13]
	s_add_i32 m0, m0, 0x2000
	s_nop 0
	global_load_lds_dwordx4 v128, s[12:13]
	s_add_u32 s12, s54, 0x80
	s_addc_u32 s13, s55, 0
	s_mov_b32 m0, s77
	s_nop 0
	global_load_lds_dwordx4 v132, s[12:13]
	s_mov_b32 m0, s78
	s_nop 0
	global_load_lds_dwordx4 v130, s[12:13]
	s_waitcnt vmcnt(8)
	s_waitcnt lgkmcnt(0)
	s_barrier
	s_setprio 1
	v_mfma_f32_16x16x32_bf16 v[60:63], v[142:145], v[174:177], v[60:63]
	v_mfma_f32_16x16x32_bf16 v[52:55], v[150:153], v[174:177], v[52:55]
	v_mfma_f32_16x16x32_bf16 v[44:47], v[142:145], v[182:185], v[44:47]
	v_mfma_f32_16x16x32_bf16 v[36:39], v[150:153], v[182:185], v[36:39]
	v_mfma_f32_16x16x32_bf16 v[28:31], v[142:145], v[194:197], v[28:31]
	v_mfma_f32_16x16x32_bf16 v[20:23], v[150:153], v[194:197], v[20:23]
	v_mfma_f32_16x16x32_bf16 v[12:15], v[142:145], v[202:205], v[12:15]
	v_mfma_f32_16x16x32_bf16 v[4:7], v[150:153], v[202:205], v[4:7]
	v_mfma_f32_16x16x32_bf16 v[60:63], v[146:149], v[178:181], v[60:63]
	v_mfma_f32_16x16x32_bf16 v[52:55], v[154:157], v[178:181], v[52:55]
	v_mfma_f32_16x16x32_bf16 v[44:47], v[146:149], v[186:189], v[44:47]
	v_mfma_f32_16x16x32_bf16 v[36:39], v[154:157], v[186:189], v[36:39]
	v_mfma_f32_16x16x32_bf16 v[28:31], v[146:149], v[198:201], v[28:31]
	v_mfma_f32_16x16x32_bf16 v[20:23], v[154:157], v[198:201], v[20:23]
	v_mfma_f32_16x16x32_bf16 v[12:15], v[146:149], v[212:215], v[12:15]
	v_mfma_f32_16x16x32_bf16 v[4:7], v[154:157], v[212:215], v[4:7]
	v_mfma_f32_16x16x32_bf16 v[56:59], v[158:161], v[174:177], v[56:59]
	v_mfma_f32_16x16x32_bf16 v[48:51], v[166:169], v[174:177], v[48:51]
	v_mfma_f32_16x16x32_bf16 v[40:43], v[158:161], v[182:185], v[40:43]
	v_mfma_f32_16x16x32_bf16 v[32:35], v[166:169], v[182:185], v[32:35]
	v_mfma_f32_16x16x32_bf16 v[24:27], v[158:161], v[194:197], v[24:27]
	v_mfma_f32_16x16x32_bf16 v[16:19], v[166:169], v[194:197], v[16:19]
	v_mfma_f32_16x16x32_bf16 v[8:11], v[158:161], v[202:205], v[8:11]
	v_mfma_f32_16x16x32_bf16 v[0:3], v[166:169], v[202:205], v[0:3]
	v_mfma_f32_16x16x32_bf16 v[56:59], v[162:165], v[178:181], v[56:59]
	v_mfma_f32_16x16x32_bf16 v[48:51], v[170:173], v[178:181], v[48:51]
	v_mfma_f32_16x16x32_bf16 v[40:43], v[162:165], v[186:189], v[40:43]
	v_mfma_f32_16x16x32_bf16 v[32:35], v[170:173], v[186:189], v[32:35]
	v_mfma_f32_16x16x32_bf16 v[24:27], v[162:165], v[198:201], v[24:27]
	v_mfma_f32_16x16x32_bf16 v[16:19], v[170:173], v[198:201], v[16:19]
	v_mfma_f32_16x16x32_bf16 v[8:11], v[162:165], v[212:215], v[8:11]
	v_mfma_f32_16x16x32_bf16 v[0:3], v[170:173], v[212:215], v[0:3]
	s_setprio 0
	s_barrier
	s_add_u32 s28, s28, 0x100
	s_addc_u32 s29, s29, 0
	s_add_u32 s18, s18, 0x100
	s_addc_u32 s19, s19, 0
	s_cmp_ge_u32 s21, s79
	s_mov_b32 s20, s21
	s_cbranch_scc0 .LBB0_137
	s_and_b64 vcc, exec, s[50:51]
	s_cbranch_vccz .LBB0_140

.LBB0_161:
	s_add_i32 s21, s20, 2
	s_add_u32 s12, s28, 0x80
	s_addc_u32 s13, s29, 0
	s_add_i32 s36, 0, 0x10000
	s_cmp_eq_u32 s85, s20
	s_cselect_b32 s59, s5, s13
	s_cselect_b32 s58, s4, s12
	v_add_u32_e32 v138, s36, v141
	s_cselect_b32 s13, s57, s19
	s_cselect_b32 s12, s56, s18
	s_add_i32 s20, 0, 0x14000
	ds_read_b128 v[148:151], v138
	ds_read_b128 v[152:155], v138 offset:1024
	ds_read_b128 v[156:159], v138 offset:2048
	ds_read_b128 v[160:163], v138 offset:3072
	v_add_u32_e32 v138, s20, v141
	ds_read_b128 v[164:167], v138
	ds_read_b128 v[168:171], v138 offset:1024
	ds_read_b128 v[172:175], v138 offset:2048
	ds_read_b128 v[176:179], v138 offset:3072
	s_add_i32 m0, s78, 0xc000
	ds_read_b128 v[180:183], v147
	ds_read_b128 v[184:187], v147 offset:1024
	ds_read_b128 v[188:191], v147 offset:2048
	ds_read_b128 v[194:197], v147 offset:3072
	ds_read_b128 v[198:201], v147 offset:4096
	ds_read_b128 v[202:205], v147 offset:5120
	ds_read_b128 v[212:215], v147 offset:6144
	ds_read_b128 v[242:245], v147 offset:7168
	global_load_lds_dwordx4 v134, s[28:29]
	s_add_i32 m0, s78, 0xe000
	s_nop 0
	global_load_lds_dwordx4 v136, s[28:29]
	s_waitcnt vmcnt(8)
	s_waitcnt lgkmcnt(0)
	s_barrier
	s_setprio 1
	v_mfma_f32_16x16x32_bf16 v[124:127], v[148:151], v[180:183], v[124:127]
	v_mfma_f32_16x16x32_bf16 v[120:123], v[156:159], v[180:183], v[120:123]
	v_mfma_f32_16x16x32_bf16 v[108:111], v[148:151], v[188:191], v[108:111]
	v_mfma_f32_16x16x32_bf16 v[104:107], v[156:159], v[188:191], v[104:107]
	v_mfma_f32_16x16x32_bf16 v[92:95], v[148:151], v[198:201], v[92:95]
	v_mfma_f32_16x16x32_bf16 v[88:91], v[156:159], v[198:201], v[88:91]
	v_mfma_f32_16x16x32_bf16 v[76:79], v[148:151], v[212:215], v[76:79]
	v_mfma_f32_16x16x32_bf16 v[72:75], v[156:159], v[212:215], v[72:75]
	v_mfma_f32_16x16x32_bf16 v[124:127], v[152:155], v[184:187], v[124:127]
	v_mfma_f32_16x16x32_bf16 v[120:123], v[160:163], v[184:187], v[120:123]
	v_mfma_f32_16x16x32_bf16 v[108:111], v[152:155], v[194:197], v[108:111]
	v_mfma_f32_16x16x32_bf16 v[104:107], v[160:163], v[194:197], v[104:107]
	v_mfma_f32_16x16x32_bf16 v[92:95], v[152:155], v[202:205], v[92:95]
	v_mfma_f32_16x16x32_bf16 v[88:91], v[160:163], v[202:205], v[88:91]
	v_mfma_f32_16x16x32_bf16 v[76:79], v[152:155], v[242:245], v[76:79]
	v_mfma_f32_16x16x32_bf16 v[72:75], v[160:163], v[242:245], v[72:75]
	v_mfma_f32_16x16x32_bf16 v[116:119], v[164:167], v[180:183], v[116:119]
	v_mfma_f32_16x16x32_bf16 v[112:115], v[172:175], v[180:183], v[112:115]
	v_mfma_f32_16x16x32_bf16 v[100:103], v[164:167], v[188:191], v[100:103]
	v_mfma_f32_16x16x32_bf16 v[96:99], v[172:175], v[188:191], v[96:99]
	v_mfma_f32_16x16x32_bf16 v[84:87], v[164:167], v[198:201], v[84:87]
	v_mfma_f32_16x16x32_bf16 v[80:83], v[172:175], v[198:201], v[80:83]
	v_mfma_f32_16x16x32_bf16 v[68:71], v[164:167], v[212:215], v[68:71]
	v_mfma_f32_16x16x32_bf16 v[64:67], v[172:175], v[212:215], v[64:67]
	v_mfma_f32_16x16x32_bf16 v[116:119], v[168:171], v[184:187], v[116:119]
	v_mfma_f32_16x16x32_bf16 v[112:115], v[176:179], v[184:187], v[112:115]
	v_mfma_f32_16x16x32_bf16 v[100:103], v[168:171], v[194:197], v[100:103]
	v_mfma_f32_16x16x32_bf16 v[96:99], v[176:179], v[194:197], v[96:99]
	v_mfma_f32_16x16x32_bf16 v[84:87], v[168:171], v[202:205], v[84:87]
	v_mfma_f32_16x16x32_bf16 v[80:83], v[176:179], v[202:205], v[80:83]
	v_mfma_f32_16x16x32_bf16 v[68:71], v[168:171], v[242:245], v[68:71]
	v_mfma_f32_16x16x32_bf16 v[64:67], v[176:179], v[242:245], v[64:67]
	s_setprio 0
	s_barrier
	s_add_i32 s36, s36, s72
	s_mov_b64 vcc, s[12:13]
	s_mov_b32 m0, s36
	ds_read_b128 v[180:183], v147 offset:16384
	ds_read_b128 v[184:187], v147 offset:17408
	ds_read_b128 v[188:191], v147 offset:18432
	ds_read_b128 v[194:197], v147 offset:19456
	ds_read_b128 v[198:201], v147 offset:20480
	ds_read_b128 v[202:205], v147 offset:21504
	ds_read_b128 v[212:215], v147 offset:22528
	ds_read_b128 v[242:245], v147 offset:23552
	global_load_lds_dwordx4 v192, s[12:13]
	s_add_i32 m0, s36, 0x2000
	s_add_i32 s20, s20, s72
	global_load_lds_dwordx4 v128, s[12:13]
	s_add_u32 s12, s12, s70
	s_addc_u32 s13, s13, 0
	s_mov_b32 m0, s20
	s_nop 0
	global_load_lds_dwordx4 v192, s[12:13]
	s_add_i32 m0, s20, 0x2000
	s_nop 0
	global_load_lds_dwordx4 v128, s[12:13]
	s_mov_b32 m0, s78
	s_nop 0
	global_load_lds_dwordx4 v132, s[58:59]
	s_mov_b32 m0, s79
	s_nop 0
	global_load_lds_dwordx4 v130, s[58:59]
	s_waitcnt vmcnt(8)
	s_waitcnt lgkmcnt(0)
	s_barrier
	s_setprio 1
	v_mfma_f32_16x16x32_bf16 v[60:63], v[148:151], v[180:183], v[60:63]
	v_mfma_f32_16x16x32_bf16 v[56:59], v[156:159], v[180:183], v[56:59]
	v_mfma_f32_16x16x32_bf16 v[44:47], v[148:151], v[188:191], v[44:47]
	v_mfma_f32_16x16x32_bf16 v[40:43], v[156:159], v[188:191], v[40:43]
	v_mfma_f32_16x16x32_bf16 v[28:31], v[148:151], v[198:201], v[28:31]
	v_mfma_f32_16x16x32_bf16 v[24:27], v[156:159], v[198:201], v[24:27]
	v_mfma_f32_16x16x32_bf16 v[12:15], v[148:151], v[212:215], v[12:15]
	v_mfma_f32_16x16x32_bf16 v[8:11], v[156:159], v[212:215], v[8:11]
	v_mfma_f32_16x16x32_bf16 v[60:63], v[152:155], v[184:187], v[60:63]
	v_mfma_f32_16x16x32_bf16 v[56:59], v[160:163], v[184:187], v[56:59]
	v_mfma_f32_16x16x32_bf16 v[44:47], v[152:155], v[194:197], v[44:47]
	v_mfma_f32_16x16x32_bf16 v[40:43], v[160:163], v[194:197], v[40:43]
	v_mfma_f32_16x16x32_bf16 v[28:31], v[152:155], v[202:205], v[28:31]
	v_mfma_f32_16x16x32_bf16 v[24:27], v[160:163], v[202:205], v[24:27]
	v_mfma_f32_16x16x32_bf16 v[12:15], v[152:155], v[242:245], v[12:15]
	v_mfma_f32_16x16x32_bf16 v[8:11], v[160:163], v[242:245], v[8:11]
	v_mfma_f32_16x16x32_bf16 v[52:55], v[164:167], v[180:183], v[52:55]
	v_mfma_f32_16x16x32_bf16 v[48:51], v[172:175], v[180:183], v[48:51]
	v_mfma_f32_16x16x32_bf16 v[36:39], v[164:167], v[188:191], v[36:39]
	v_mfma_f32_16x16x32_bf16 v[32:35], v[172:175], v[188:191], v[32:35]
	v_mfma_f32_16x16x32_bf16 v[20:23], v[164:167], v[198:201], v[20:23]
	v_mfma_f32_16x16x32_bf16 v[16:19], v[172:175], v[198:201], v[16:19]
	v_mfma_f32_16x16x32_bf16 v[4:7], v[164:167], v[212:215], v[4:7]
	v_mfma_f32_16x16x32_bf16 v[0:3], v[172:175], v[212:215], v[0:3]
	v_mfma_f32_16x16x32_bf16 v[52:55], v[168:171], v[184:187], v[52:55]
	v_mfma_f32_16x16x32_bf16 v[48:51], v[176:179], v[184:187], v[48:51]
	v_mfma_f32_16x16x32_bf16 v[36:39], v[168:171], v[194:197], v[36:39]
	v_mfma_f32_16x16x32_bf16 v[32:35], v[176:179], v[194:197], v[32:35]
	v_mfma_f32_16x16x32_bf16 v[20:23], v[168:171], v[202:205], v[20:23]
	v_mfma_f32_16x16x32_bf16 v[16:19], v[176:179], v[202:205], v[16:19]
	v_mfma_f32_16x16x32_bf16 v[4:7], v[168:171], v[242:245], v[4:7]
	v_mfma_f32_16x16x32_bf16 v[0:3], v[176:179], v[242:245], v[0:3]
	s_setprio 0
	s_barrier
	s_add_i32 s20, 0, 0x18000
	v_add_u32_e32 v138, s20, v141
	s_add_i32 s36, 0, 0x1c000
	ds_read_b128 v[148:151], v138
	ds_read_b128 v[152:155], v138 offset:1024
	ds_read_b128 v[156:159], v138 offset:2048
	ds_read_b128 v[160:163], v138 offset:3072
	v_add_u32_e32 v138, s36, v141
	ds_read_b128 v[164:167], v138
	ds_read_b128 v[168:171], v138 offset:1024
	ds_read_b128 v[172:175], v138 offset:2048
	ds_read_b128 v[176:179], v138 offset:3072
	s_add_u32 s12, s58, s34
	s_addc_u32 s13, s59, 0
	s_mov_b32 m0, s80
	ds_read_b128 v[180:183], v147 offset:32768
	ds_read_b128 v[184:187], v147 offset:33792
	ds_read_b128 v[188:191], v147 offset:34816
	ds_read_b128 v[194:197], v147 offset:35840
	ds_read_b128 v[198:201], v147 offset:36864
	ds_read_b128 v[202:205], v147 offset:37888
	ds_read_b128 v[212:215], v147 offset:38912
	ds_read_b128 v[242:245], v147 offset:39936
	global_load_lds_dwordx4 v132, s[12:13]
	s_mov_b32 m0, s81
	s_nop 0
	global_load_lds_dwordx4 v130, s[12:13]
	s_waitcnt vmcnt(8)
	s_waitcnt lgkmcnt(0)
	s_barrier
	s_setprio 1
	v_mfma_f32_16x16x32_bf16 v[124:127], v[148:151], v[180:183], v[124:127]
	v_mfma_f32_16x16x32_bf16 v[120:123], v[156:159], v[180:183], v[120:123]
	v_mfma_f32_16x16x32_bf16 v[108:111], v[148:151], v[188:191], v[108:111]
	v_mfma_f32_16x16x32_bf16 v[104:107], v[156:159], v[188:191], v[104:107]
	v_mfma_f32_16x16x32_bf16 v[92:95], v[148:151], v[198:201], v[92:95]
	v_mfma_f32_16x16x32_bf16 v[88:91], v[156:159], v[198:201], v[88:91]
	v_mfma_f32_16x16x32_bf16 v[76:79], v[148:151], v[212:215], v[76:79]
	v_mfma_f32_16x16x32_bf16 v[72:75], v[156:159], v[212:215], v[72:75]
	v_mfma_f32_16x16x32_bf16 v[124:127], v[152:155], v[184:187], v[124:127]
	v_mfma_f32_16x16x32_bf16 v[120:123], v[160:163], v[184:187], v[120:123]
	v_mfma_f32_16x16x32_bf16 v[108:111], v[152:155], v[194:197], v[108:111]
	v_mfma_f32_16x16x32_bf16 v[104:107], v[160:163], v[194:197], v[104:107]
	v_mfma_f32_16x16x32_bf16 v[92:95], v[152:155], v[202:205], v[92:95]
	v_mfma_f32_16x16x32_bf16 v[88:91], v[160:163], v[202:205], v[88:91]
	v_mfma_f32_16x16x32_bf16 v[76:79], v[152:155], v[242:245], v[76:79]
	v_mfma_f32_16x16x32_bf16 v[72:75], v[160:163], v[242:245], v[72:75]
	v_mfma_f32_16x16x32_bf16 v[116:119], v[164:167], v[180:183], v[116:119]
	v_mfma_f32_16x16x32_bf16 v[112:115], v[172:175], v[180:183], v[112:115]
	v_mfma_f32_16x16x32_bf16 v[100:103], v[164:167], v[188:191], v[100:103]
	v_mfma_f32_16x16x32_bf16 v[96:99], v[172:175], v[188:191], v[96:99]
	v_mfma_f32_16x16x32_bf16 v[84:87], v[164:167], v[198:201], v[84:87]
	v_mfma_f32_16x16x32_bf16 v[80:83], v[172:175], v[198:201], v[80:83]
	v_mfma_f32_16x16x32_bf16 v[68:71], v[164:167], v[212:215], v[68:71]
	v_mfma_f32_16x16x32_bf16 v[64:67], v[172:175], v[212:215], v[64:67]
	v_mfma_f32_16x16x32_bf16 v[116:119], v[168:171], v[184:187], v[116:119]
	v_mfma_f32_16x16x32_bf16 v[112:115], v[176:179], v[184:187], v[112:115]
	v_mfma_f32_16x16x32_bf16 v[100:103], v[168:171], v[194:197], v[100:103]
	v_mfma_f32_16x16x32_bf16 v[96:99], v[176:179], v[194:197], v[96:99]
	v_mfma_f32_16x16x32_bf16 v[84:87], v[168:171], v[202:205], v[84:87]
	v_mfma_f32_16x16x32_bf16 v[80:83], v[176:179], v[202:205], v[80:83]
	v_mfma_f32_16x16x32_bf16 v[68:71], v[168:171], v[242:245], v[68:71]
	v_mfma_f32_16x16x32_bf16 v[64:67], v[176:179], v[242:245], v[64:67]
	s_setprio 0
	s_barrier
	s_add_i32 m0, s20, s72
	s_add_u32 s12, vcc_lo, 0x80
	s_addc_u32 s13, vcc_hi, 0
	ds_read_b128 v[180:183], v147 offset:49152
	ds_read_b128 v[184:187], v147 offset:50176
	ds_read_b128 v[188:191], v147 offset:51200
	ds_read_b128 v[194:197], v147 offset:52224
	ds_read_b128 v[198:201], v147 offset:53248
	ds_read_b128 v[202:205], v147 offset:54272
	ds_read_b128 v[212:215], v147 offset:55296
	ds_read_b128 v[242:245], v147 offset:56320
	global_load_lds_dwordx4 v192, s[12:13]
	s_add_i32 m0, m0, 0x2000
	s_nop 0
	global_load_lds_dwordx4 v128, s[12:13]
	s_add_u32 s12, s12, s70
	s_addc_u32 s13, s13, 0
	s_add_i32 m0, s36, s72
	s_nop 0
	global_load_lds_dwordx4 v192, s[12:13]
	s_add_i32 m0, m0, 0x2000
	s_nop 0
	global_load_lds_dwordx4 v128, s[12:13]
	s_add_u32 s12, s58, 0x80
	s_addc_u32 s13, s59, 0
	s_mov_b32 m0, s82
	s_nop 0
	global_load_lds_dwordx4 v132, s[12:13]
	s_mov_b32 m0, s83
	s_nop 0
	global_load_lds_dwordx4 v130, s[12:13]
	s_waitcnt vmcnt(8)
	s_waitcnt lgkmcnt(0)
	s_barrier
	s_setprio 1
	v_mfma_f32_16x16x32_bf16 v[60:63], v[148:151], v[180:183], v[60:63]
	v_mfma_f32_16x16x32_bf16 v[56:59], v[156:159], v[180:183], v[56:59]
	v_mfma_f32_16x16x32_bf16 v[44:47], v[148:151], v[188:191], v[44:47]
	v_mfma_f32_16x16x32_bf16 v[40:43], v[156:159], v[188:191], v[40:43]
	v_mfma_f32_16x16x32_bf16 v[28:31], v[148:151], v[198:201], v[28:31]
	v_mfma_f32_16x16x32_bf16 v[24:27], v[156:159], v[198:201], v[24:27]
	v_mfma_f32_16x16x32_bf16 v[12:15], v[148:151], v[212:215], v[12:15]
	v_mfma_f32_16x16x32_bf16 v[8:11], v[156:159], v[212:215], v[8:11]
	v_mfma_f32_16x16x32_bf16 v[60:63], v[152:155], v[184:187], v[60:63]
	v_mfma_f32_16x16x32_bf16 v[56:59], v[160:163], v[184:187], v[56:59]
	v_mfma_f32_16x16x32_bf16 v[44:47], v[152:155], v[194:197], v[44:47]
	v_mfma_f32_16x16x32_bf16 v[40:43], v[160:163], v[194:197], v[40:43]
	v_mfma_f32_16x16x32_bf16 v[28:31], v[152:155], v[202:205], v[28:31]
	v_mfma_f32_16x16x32_bf16 v[24:27], v[160:163], v[202:205], v[24:27]
	v_mfma_f32_16x16x32_bf16 v[12:15], v[152:155], v[242:245], v[12:15]
	v_mfma_f32_16x16x32_bf16 v[8:11], v[160:163], v[242:245], v[8:11]
	v_mfma_f32_16x16x32_bf16 v[52:55], v[164:167], v[180:183], v[52:55]
	v_mfma_f32_16x16x32_bf16 v[48:51], v[172:175], v[180:183], v[48:51]
	v_mfma_f32_16x16x32_bf16 v[36:39], v[164:167], v[188:191], v[36:39]
	v_mfma_f32_16x16x32_bf16 v[32:35], v[172:175], v[188:191], v[32:35]
	v_mfma_f32_16x16x32_bf16 v[20:23], v[164:167], v[198:201], v[20:23]
	v_mfma_f32_16x16x32_bf16 v[16:19], v[172:175], v[198:201], v[16:19]
	v_mfma_f32_16x16x32_bf16 v[4:7], v[164:167], v[212:215], v[4:7]
	v_mfma_f32_16x16x32_bf16 v[0:3], v[172:175], v[212:215], v[0:3]
	v_mfma_f32_16x16x32_bf16 v[52:55], v[168:171], v[184:187], v[52:55]
	v_mfma_f32_16x16x32_bf16 v[48:51], v[176:179], v[184:187], v[48:51]
	v_mfma_f32_16x16x32_bf16 v[36:39], v[168:171], v[194:197], v[36:39]
	v_mfma_f32_16x16x32_bf16 v[32:35], v[176:179], v[194:197], v[32:35]
	v_mfma_f32_16x16x32_bf16 v[20:23], v[168:171], v[202:205], v[20:23]
	v_mfma_f32_16x16x32_bf16 v[16:19], v[176:179], v[202:205], v[16:19]
	v_mfma_f32_16x16x32_bf16 v[4:7], v[168:171], v[242:245], v[4:7]
	v_mfma_f32_16x16x32_bf16 v[0:3], v[176:179], v[242:245], v[0:3]
	s_setprio 0
	s_barrier
	s_add_u32 s28, s28, 0x100
	s_addc_u32 s29, s29, 0
	s_add_u32 s18, s18, 0x100
	s_addc_u32 s19, s19, 0
	s_cmp_ge_u32 s21, s84
	s_mov_b32 s20, s21
	s_cbranch_scc0 .LBB0_161
	s_and_b64 vcc, exec, s[50:51]
	s_cbranch_vccz .LBB0_164

.LBB0_188:
	s_add_i32 s21, s20, 2
	s_add_u32 s12, s28, 0x80
	s_addc_u32 s13, s29, 0
	s_add_i32 s36, 0, 0x10000
	s_cmp_eq_u32 s67, s20
	s_cselect_b32 s57, s5, s13
	s_cselect_b32 s56, s4, s12
	s_cselect_b32 s13, s55, s19
	s_cselect_b32 s12, s54, s18
	s_add_i32 s20, 0, 0x14000
	v_add_u32_e32 v154, s36, v139
	v_add_u32_e32 v170, s20, v139
	ds_read_b128 v[142:145], v154
	ds_read_b128 v[146:149], v154 offset:1024
	ds_read_b128 v[150:153], v154 offset:2048
	ds_read_b128 v[154:157], v154 offset:3072
	ds_read_b128 v[158:161], v170
	ds_read_b128 v[162:165], v170 offset:1024
	ds_read_b128 v[166:169], v170 offset:2048
	ds_read_b128 v[170:173], v170 offset:3072
	s_add_i32 m0, s68, 0xc000
	ds_read_b128 v[174:177], v141
	ds_read_b128 v[178:181], v141 offset:1024
	ds_read_b128 v[182:185], v141 offset:2048
	ds_read_b128 v[186:189], v141 offset:3072
	ds_read_b128 v[194:197], v141 offset:4096
	ds_read_b128 v[198:201], v141 offset:5120
	ds_read_b128 v[202:205], v141 offset:6144
	ds_read_b128 v[212:215], v141 offset:7168
	global_load_lds_dwordx4 v134, s[28:29]
	s_add_i32 m0, s68, 0xe000
	s_nop 0
	global_load_lds_dwordx4 v136, s[28:29]
	s_waitcnt vmcnt(8)
	s_waitcnt lgkmcnt(0)
	s_barrier
	s_setprio 1
	v_mfma_f32_16x16x32_bf16 v[124:127], v[142:145], v[174:177], v[124:127]
	v_mfma_f32_16x16x32_bf16 v[120:123], v[150:153], v[174:177], v[120:123]
	v_mfma_f32_16x16x32_bf16 v[108:111], v[142:145], v[182:185], v[108:111]
	v_mfma_f32_16x16x32_bf16 v[104:107], v[150:153], v[182:185], v[104:107]
	v_mfma_f32_16x16x32_bf16 v[92:95], v[142:145], v[194:197], v[92:95]
	v_mfma_f32_16x16x32_bf16 v[88:91], v[150:153], v[194:197], v[88:91]
	v_mfma_f32_16x16x32_bf16 v[76:79], v[142:145], v[202:205], v[76:79]
	v_mfma_f32_16x16x32_bf16 v[72:75], v[150:153], v[202:205], v[72:75]
	v_mfma_f32_16x16x32_bf16 v[124:127], v[146:149], v[178:181], v[124:127]
	v_mfma_f32_16x16x32_bf16 v[120:123], v[154:157], v[178:181], v[120:123]
	v_mfma_f32_16x16x32_bf16 v[108:111], v[146:149], v[186:189], v[108:111]
	v_mfma_f32_16x16x32_bf16 v[104:107], v[154:157], v[186:189], v[104:107]
	v_mfma_f32_16x16x32_bf16 v[92:95], v[146:149], v[198:201], v[92:95]
	v_mfma_f32_16x16x32_bf16 v[88:91], v[154:157], v[198:201], v[88:91]
	v_mfma_f32_16x16x32_bf16 v[76:79], v[146:149], v[212:215], v[76:79]
	v_mfma_f32_16x16x32_bf16 v[72:75], v[154:157], v[212:215], v[72:75]
	v_mfma_f32_16x16x32_bf16 v[116:119], v[158:161], v[174:177], v[116:119]
	v_mfma_f32_16x16x32_bf16 v[112:115], v[166:169], v[174:177], v[112:115]
	v_mfma_f32_16x16x32_bf16 v[100:103], v[158:161], v[182:185], v[100:103]
	v_mfma_f32_16x16x32_bf16 v[96:99], v[166:169], v[182:185], v[96:99]
	v_mfma_f32_16x16x32_bf16 v[84:87], v[158:161], v[194:197], v[84:87]
	v_mfma_f32_16x16x32_bf16 v[80:83], v[166:169], v[194:197], v[80:83]
	v_mfma_f32_16x16x32_bf16 v[68:71], v[158:161], v[202:205], v[68:71]
	v_mfma_f32_16x16x32_bf16 v[64:67], v[166:169], v[202:205], v[64:67]
	v_mfma_f32_16x16x32_bf16 v[116:119], v[162:165], v[178:181], v[116:119]
	v_mfma_f32_16x16x32_bf16 v[112:115], v[170:173], v[178:181], v[112:115]
	v_mfma_f32_16x16x32_bf16 v[100:103], v[162:165], v[186:189], v[100:103]
	v_mfma_f32_16x16x32_bf16 v[96:99], v[170:173], v[186:189], v[96:99]
	v_mfma_f32_16x16x32_bf16 v[84:87], v[162:165], v[198:201], v[84:87]
	v_mfma_f32_16x16x32_bf16 v[80:83], v[170:173], v[198:201], v[80:83]
	v_mfma_f32_16x16x32_bf16 v[68:71], v[162:165], v[212:215], v[68:71]
	v_mfma_f32_16x16x32_bf16 v[64:67], v[170:173], v[212:215], v[64:67]
	s_setprio 0
	s_barrier
	s_add_i32 s36, s36, s70
	s_mov_b64 vcc, s[12:13]
	s_mov_b32 m0, s36
	ds_read_b128 v[174:177], v141 offset:16384
	ds_read_b128 v[178:181], v141 offset:17408
	ds_read_b128 v[182:185], v141 offset:18432
	ds_read_b128 v[186:189], v141 offset:19456
	ds_read_b128 v[194:197], v141 offset:20480
	ds_read_b128 v[198:201], v141 offset:21504
	ds_read_b128 v[202:205], v141 offset:22528
	ds_read_b128 v[212:215], v141 offset:23552
	global_load_lds_dwordx4 v192, s[12:13]
	s_add_i32 m0, s36, 0x2000
	s_add_i32 s20, s20, s70
	global_load_lds_dwordx4 v128, s[12:13]
	s_add_u32 s12, s12, s58
	s_addc_u32 s13, s13, 0
	s_mov_b32 m0, s20
	s_nop 0
	global_load_lds_dwordx4 v192, s[12:13]
	s_add_i32 m0, s20, 0x2000
	s_nop 0
	global_load_lds_dwordx4 v128, s[12:13]
	s_mov_b32 m0, s68
	s_nop 0
	global_load_lds_dwordx4 v132, s[56:57]
	s_mov_b32 m0, s75
	s_nop 0
	global_load_lds_dwordx4 v130, s[56:57]
	s_waitcnt vmcnt(8)
	s_waitcnt lgkmcnt(0)
	s_barrier
	s_setprio 1
	v_mfma_f32_16x16x32_bf16 v[60:63], v[142:145], v[174:177], v[60:63]
	v_mfma_f32_16x16x32_bf16 v[56:59], v[150:153], v[174:177], v[56:59]
	v_mfma_f32_16x16x32_bf16 v[44:47], v[142:145], v[182:185], v[44:47]
	v_mfma_f32_16x16x32_bf16 v[40:43], v[150:153], v[182:185], v[40:43]
	v_mfma_f32_16x16x32_bf16 v[28:31], v[142:145], v[194:197], v[28:31]
	v_mfma_f32_16x16x32_bf16 v[24:27], v[150:153], v[194:197], v[24:27]
	v_mfma_f32_16x16x32_bf16 v[12:15], v[142:145], v[202:205], v[12:15]
	v_mfma_f32_16x16x32_bf16 v[8:11], v[150:153], v[202:205], v[8:11]
	v_mfma_f32_16x16x32_bf16 v[60:63], v[146:149], v[178:181], v[60:63]
	v_mfma_f32_16x16x32_bf16 v[56:59], v[154:157], v[178:181], v[56:59]
	v_mfma_f32_16x16x32_bf16 v[44:47], v[146:149], v[186:189], v[44:47]
	v_mfma_f32_16x16x32_bf16 v[40:43], v[154:157], v[186:189], v[40:43]
	v_mfma_f32_16x16x32_bf16 v[28:31], v[146:149], v[198:201], v[28:31]
	v_mfma_f32_16x16x32_bf16 v[24:27], v[154:157], v[198:201], v[24:27]
	v_mfma_f32_16x16x32_bf16 v[12:15], v[146:149], v[212:215], v[12:15]
	v_mfma_f32_16x16x32_bf16 v[8:11], v[154:157], v[212:215], v[8:11]
	v_mfma_f32_16x16x32_bf16 v[52:55], v[158:161], v[174:177], v[52:55]
	v_mfma_f32_16x16x32_bf16 v[48:51], v[166:169], v[174:177], v[48:51]
	v_mfma_f32_16x16x32_bf16 v[36:39], v[158:161], v[182:185], v[36:39]
	v_mfma_f32_16x16x32_bf16 v[32:35], v[166:169], v[182:185], v[32:35]
	v_mfma_f32_16x16x32_bf16 v[20:23], v[158:161], v[194:197], v[20:23]
	v_mfma_f32_16x16x32_bf16 v[16:19], v[166:169], v[194:197], v[16:19]
	v_mfma_f32_16x16x32_bf16 v[4:7], v[158:161], v[202:205], v[4:7]
	v_mfma_f32_16x16x32_bf16 v[0:3], v[166:169], v[202:205], v[0:3]
	v_mfma_f32_16x16x32_bf16 v[52:55], v[162:165], v[178:181], v[52:55]
	v_mfma_f32_16x16x32_bf16 v[48:51], v[170:173], v[178:181], v[48:51]
	v_mfma_f32_16x16x32_bf16 v[36:39], v[162:165], v[186:189], v[36:39]
	v_mfma_f32_16x16x32_bf16 v[32:35], v[170:173], v[186:189], v[32:35]
	v_mfma_f32_16x16x32_bf16 v[20:23], v[162:165], v[198:201], v[20:23]
	v_mfma_f32_16x16x32_bf16 v[16:19], v[170:173], v[198:201], v[16:19]
	v_mfma_f32_16x16x32_bf16 v[4:7], v[162:165], v[212:215], v[4:7]
	v_mfma_f32_16x16x32_bf16 v[0:3], v[170:173], v[212:215], v[0:3]
	s_setprio 0
	s_barrier
	s_add_i32 s20, 0, 0x18000
	s_add_i32 s36, 0, 0x1c000
	v_add_u32_e32 v154, s20, v139
	v_add_u32_e32 v170, s36, v139
	ds_read_b128 v[142:145], v154
	ds_read_b128 v[146:149], v154 offset:1024
	ds_read_b128 v[150:153], v154 offset:2048
	ds_read_b128 v[154:157], v154 offset:3072
	ds_read_b128 v[158:161], v170
	ds_read_b128 v[162:165], v170 offset:1024
	ds_read_b128 v[166:169], v170 offset:2048
	ds_read_b128 v[170:173], v170 offset:3072
	s_add_u32 s12, s56, s34
	s_addc_u32 s13, s57, 0
	s_mov_b32 m0, s76
	ds_read_b128 v[174:177], v141 offset:32768
	ds_read_b128 v[178:181], v141 offset:33792
	ds_read_b128 v[182:185], v141 offset:34816
	ds_read_b128 v[186:189], v141 offset:35840
	ds_read_b128 v[194:197], v141 offset:36864
	ds_read_b128 v[198:201], v141 offset:37888
	ds_read_b128 v[202:205], v141 offset:38912
	ds_read_b128 v[212:215], v141 offset:39936
	global_load_lds_dwordx4 v132, s[12:13]
	s_mov_b32 m0, s77
	s_nop 0
	global_load_lds_dwordx4 v130, s[12:13]
	s_waitcnt vmcnt(8)
	s_waitcnt lgkmcnt(0)
	s_barrier
	s_setprio 1
	v_mfma_f32_16x16x32_bf16 v[124:127], v[142:145], v[174:177], v[124:127]
	v_mfma_f32_16x16x32_bf16 v[120:123], v[150:153], v[174:177], v[120:123]
	v_mfma_f32_16x16x32_bf16 v[108:111], v[142:145], v[182:185], v[108:111]
	v_mfma_f32_16x16x32_bf16 v[104:107], v[150:153], v[182:185], v[104:107]
	v_mfma_f32_16x16x32_bf16 v[92:95], v[142:145], v[194:197], v[92:95]
	v_mfma_f32_16x16x32_bf16 v[88:91], v[150:153], v[194:197], v[88:91]
	v_mfma_f32_16x16x32_bf16 v[76:79], v[142:145], v[202:205], v[76:79]
	v_mfma_f32_16x16x32_bf16 v[72:75], v[150:153], v[202:205], v[72:75]
	v_mfma_f32_16x16x32_bf16 v[124:127], v[146:149], v[178:181], v[124:127]
	v_mfma_f32_16x16x32_bf16 v[120:123], v[154:157], v[178:181], v[120:123]
	v_mfma_f32_16x16x32_bf16 v[108:111], v[146:149], v[186:189], v[108:111]
	v_mfma_f32_16x16x32_bf16 v[104:107], v[154:157], v[186:189], v[104:107]
	v_mfma_f32_16x16x32_bf16 v[92:95], v[146:149], v[198:201], v[92:95]
	v_mfma_f32_16x16x32_bf16 v[88:91], v[154:157], v[198:201], v[88:91]
	v_mfma_f32_16x16x32_bf16 v[76:79], v[146:149], v[212:215], v[76:79]
	v_mfma_f32_16x16x32_bf16 v[72:75], v[154:157], v[212:215], v[72:75]
	v_mfma_f32_16x16x32_bf16 v[116:119], v[158:161], v[174:177], v[116:119]
	v_mfma_f32_16x16x32_bf16 v[112:115], v[166:169], v[174:177], v[112:115]
	v_mfma_f32_16x16x32_bf16 v[100:103], v[158:161], v[182:185], v[100:103]
	v_mfma_f32_16x16x32_bf16 v[96:99], v[166:169], v[182:185], v[96:99]
	v_mfma_f32_16x16x32_bf16 v[84:87], v[158:161], v[194:197], v[84:87]
	v_mfma_f32_16x16x32_bf16 v[80:83], v[166:169], v[194:197], v[80:83]
	v_mfma_f32_16x16x32_bf16 v[68:71], v[158:161], v[202:205], v[68:71]
	v_mfma_f32_16x16x32_bf16 v[64:67], v[166:169], v[202:205], v[64:67]
	v_mfma_f32_16x16x32_bf16 v[116:119], v[162:165], v[178:181], v[116:119]
	v_mfma_f32_16x16x32_bf16 v[112:115], v[170:173], v[178:181], v[112:115]
	v_mfma_f32_16x16x32_bf16 v[100:103], v[162:165], v[186:189], v[100:103]
	v_mfma_f32_16x16x32_bf16 v[96:99], v[170:173], v[186:189], v[96:99]
	v_mfma_f32_16x16x32_bf16 v[84:87], v[162:165], v[198:201], v[84:87]
	v_mfma_f32_16x16x32_bf16 v[80:83], v[170:173], v[198:201], v[80:83]
	v_mfma_f32_16x16x32_bf16 v[68:71], v[162:165], v[212:215], v[68:71]
	v_mfma_f32_16x16x32_bf16 v[64:67], v[170:173], v[212:215], v[64:67]
	s_setprio 0
	s_barrier
	s_add_i32 m0, s20, s70
	s_add_u32 s12, vcc_lo, 0x80
	s_addc_u32 s13, vcc_hi, 0
	ds_read_b128 v[174:177], v141 offset:49152
	ds_read_b128 v[178:181], v141 offset:50176
	ds_read_b128 v[182:185], v141 offset:51200
	ds_read_b128 v[186:189], v141 offset:52224
	ds_read_b128 v[194:197], v141 offset:53248
	ds_read_b128 v[198:201], v141 offset:54272
	ds_read_b128 v[202:205], v141 offset:55296
	ds_read_b128 v[212:215], v141 offset:56320
	global_load_lds_dwordx4 v192, s[12:13]
	s_add_i32 m0, m0, 0x2000
	s_nop 0
	global_load_lds_dwordx4 v128, s[12:13]
	s_add_u32 s12, s12, s58
	s_addc_u32 s13, s13, 0
	s_add_i32 m0, s36, s70
	s_nop 0
	global_load_lds_dwordx4 v192, s[12:13]
	s_add_i32 m0, m0, 0x2000
	s_nop 0
	global_load_lds_dwordx4 v128, s[12:13]
	s_add_u32 s12, s56, 0x80
	s_addc_u32 s13, s57, 0
	s_mov_b32 m0, s78
	s_nop 0
	global_load_lds_dwordx4 v132, s[12:13]
	s_mov_b32 m0, s79
	s_nop 0
	global_load_lds_dwordx4 v130, s[12:13]
	s_waitcnt vmcnt(8)
	s_waitcnt lgkmcnt(0)
	s_barrier
	s_setprio 1
	v_mfma_f32_16x16x32_bf16 v[60:63], v[142:145], v[174:177], v[60:63]
	v_mfma_f32_16x16x32_bf16 v[56:59], v[150:153], v[174:177], v[56:59]
	v_mfma_f32_16x16x32_bf16 v[44:47], v[142:145], v[182:185], v[44:47]
	v_mfma_f32_16x16x32_bf16 v[40:43], v[150:153], v[182:185], v[40:43]
	v_mfma_f32_16x16x32_bf16 v[28:31], v[142:145], v[194:197], v[28:31]
	v_mfma_f32_16x16x32_bf16 v[24:27], v[150:153], v[194:197], v[24:27]
	v_mfma_f32_16x16x32_bf16 v[12:15], v[142:145], v[202:205], v[12:15]
	v_mfma_f32_16x16x32_bf16 v[8:11], v[150:153], v[202:205], v[8:11]
	v_mfma_f32_16x16x32_bf16 v[60:63], v[146:149], v[178:181], v[60:63]
	v_mfma_f32_16x16x32_bf16 v[56:59], v[154:157], v[178:181], v[56:59]
	v_mfma_f32_16x16x32_bf16 v[44:47], v[146:149], v[186:189], v[44:47]
	v_mfma_f32_16x16x32_bf16 v[40:43], v[154:157], v[186:189], v[40:43]
	v_mfma_f32_16x16x32_bf16 v[28:31], v[146:149], v[198:201], v[28:31]
	v_mfma_f32_16x16x32_bf16 v[24:27], v[154:157], v[198:201], v[24:27]
	v_mfma_f32_16x16x32_bf16 v[12:15], v[146:149], v[212:215], v[12:15]
	v_mfma_f32_16x16x32_bf16 v[8:11], v[154:157], v[212:215], v[8:11]
	v_mfma_f32_16x16x32_bf16 v[52:55], v[158:161], v[174:177], v[52:55]
	v_mfma_f32_16x16x32_bf16 v[48:51], v[166:169], v[174:177], v[48:51]
	v_mfma_f32_16x16x32_bf16 v[36:39], v[158:161], v[182:185], v[36:39]
	v_mfma_f32_16x16x32_bf16 v[32:35], v[166:169], v[182:185], v[32:35]
	v_mfma_f32_16x16x32_bf16 v[20:23], v[158:161], v[194:197], v[20:23]
	v_mfma_f32_16x16x32_bf16 v[16:19], v[166:169], v[194:197], v[16:19]
	v_mfma_f32_16x16x32_bf16 v[4:7], v[158:161], v[202:205], v[4:7]
	v_mfma_f32_16x16x32_bf16 v[0:3], v[166:169], v[202:205], v[0:3]
	v_mfma_f32_16x16x32_bf16 v[52:55], v[162:165], v[178:181], v[52:55]
	v_mfma_f32_16x16x32_bf16 v[48:51], v[170:173], v[178:181], v[48:51]
	v_mfma_f32_16x16x32_bf16 v[36:39], v[162:165], v[186:189], v[36:39]
	v_mfma_f32_16x16x32_bf16 v[32:35], v[170:173], v[186:189], v[32:35]
	v_mfma_f32_16x16x32_bf16 v[20:23], v[162:165], v[198:201], v[20:23]
	v_mfma_f32_16x16x32_bf16 v[16:19], v[170:173], v[198:201], v[16:19]
	v_mfma_f32_16x16x32_bf16 v[4:7], v[162:165], v[212:215], v[4:7]
	v_mfma_f32_16x16x32_bf16 v[0:3], v[170:173], v[212:215], v[0:3]
	s_setprio 0
	s_barrier
	s_add_u32 s28, s28, 0x100
	s_addc_u32 s29, s29, 0
	s_add_u32 s18, s18, 0x100
	s_addc_u32 s19, s19, 0
	s_cmp_ge_u32 s21, s80
	s_mov_b32 s20, s21
	s_cbranch_scc0 .LBB0_188
	s_and_b64 vcc, exec, s[48:49]
	s_cbranch_vccz .LBB0_191
